# GEMM K-loops: first K-tile pair peeled with srcC=0, the 128 accumulator-zeroing moves per unit removed (all six GEMM phases)
# speedup vs baseline: 1.0030x; 1.0030x over previous
.LBB0_216:
	s_ashr_i32 s17, s16, 31
	s_lshl_b64 s[18:19], s[16:17], 19
	s_add_u32 s18, s90, s18
	s_addc_u32 s19, s91, s19
	s_and_b64 s[20:21], s[6:7], exec
	s_cselect_b32 s17, s19, s25
	s_cselect_b32 s46, s18, s24
	s_ashr_i32 s15, s14, 31
	s_lshl_b64 s[20:21], s[14:15], 19
	s_add_u32 s20, s2, s20
	s_addc_u32 s21, s3, s21
	s_and_b64 s[28:29], s[6:7], exec
	s_cselect_b32 s15, s21, s27
	s_cselect_b32 s47, s20, s26
	s_add_u32 s24, s24, 0x40080
	s_addc_u32 s25, s25, 0
	s_add_u32 s48, s26, 0x100
	s_addc_u32 s49, s27, 0
	s_mov_b32 s50, -2
	s_waitcnt lgkmcnt(0)
	v_xor_b32_e32 v246, 64, v153
	v_xor_b32_e32 v247, 64, v149
	v_add_u32_e32 v248, s42, v247
	v_add_u32_e32 v249, s43, v247
	ds_read_b128 v[144:147], v151
	ds_read_b128 v[154:157], v248
	ds_read_b128 v[158:161], v151 offset:2048
	ds_read_b128 v[162:165], v248 offset:2048
	ds_read_b128 v[166:169], v152
	ds_read_b128 v[170:173], v249
	ds_read_b128 v[174:177], v152 offset:2048
	ds_read_b128 v[178:181], v249 offset:2048
	s_add_u32 s26, s24, 0xfffc0080
	s_addc_u32 s27, s25, -1
	s_cmp_eq_u32 s50, 12
	s_cselect_b32 s29, s17, s27
	s_cselect_b32 s28, s46, s26
	s_cselect_b32 s27, s15, s49
	s_cselect_b32 s26, s47, s48
	v_lshl_add_u64 v[214:215], s[24:25], 0, v[136:137]
	s_add_i32 m0, s23, 0xc000
	ds_read_b128 v[182:185], v153
	ds_read_b128 v[186:189], v246
	ds_read_b128 v[190:193], v153 offset:2048
	ds_read_b128 v[194:197], v246 offset:2048
	ds_read_b128 v[198:201], v153 offset:4096
	ds_read_b128 v[202:205], v246 offset:4096
	ds_read_b128 v[206:209], v153 offset:6144
	ds_read_b128 v[210:213], v246 offset:6144
	global_load_lds_dwordx4 v[214:215], off
	v_lshl_add_u64 v[214:215], s[24:25], 0, v[138:139]
	s_add_i32 m0, s23, 0xe000
	s_nop 0
	global_load_lds_dwordx4 v[214:215], off
	s_waitcnt vmcnt(8)
	s_waitcnt lgkmcnt(0)
	s_barrier
	s_setprio 0
	s_waitcnt lgkmcnt(0)
	v_mfma_f32_16x16x32_bf16 v[124:127], v[144:147], v[182:185], 0
	v_mfma_f32_16x16x32_bf16 v[120:123], v[158:161], v[182:185], 0
	v_mfma_f32_16x16x32_bf16 v[108:111], v[144:147], v[190:193], 0
	v_mfma_f32_16x16x32_bf16 v[104:107], v[158:161], v[190:193], 0
	v_mfma_f32_16x16x32_bf16 v[92:95], v[144:147], v[198:201], 0
	v_mfma_f32_16x16x32_bf16 v[88:91], v[158:161], v[198:201], 0
	v_mfma_f32_16x16x32_bf16 v[76:79], v[144:147], v[206:209], 0
	v_mfma_f32_16x16x32_bf16 v[72:75], v[158:161], v[206:209], 0
	v_mfma_f32_16x16x32_bf16 v[124:127], v[154:157], v[186:189], v[124:127]
	v_mfma_f32_16x16x32_bf16 v[120:123], v[162:165], v[186:189], v[120:123]
	v_mfma_f32_16x16x32_bf16 v[108:111], v[154:157], v[194:197], v[108:111]
	v_mfma_f32_16x16x32_bf16 v[104:107], v[162:165], v[194:197], v[104:107]
	v_mfma_f32_16x16x32_bf16 v[92:95], v[154:157], v[202:205], v[92:95]
	v_mfma_f32_16x16x32_bf16 v[88:91], v[162:165], v[202:205], v[88:91]
	v_mfma_f32_16x16x32_bf16 v[76:79], v[154:157], v[210:213], v[76:79]
	v_mfma_f32_16x16x32_bf16 v[72:75], v[162:165], v[210:213], v[72:75]
	s_setprio 0
	s_setprio 0
	v_mfma_f32_16x16x32_bf16 v[116:119], v[166:169], v[182:185], 0
	v_mfma_f32_16x16x32_bf16 v[112:115], v[174:177], v[182:185], 0
	v_mfma_f32_16x16x32_bf16 v[100:103], v[166:169], v[190:193], 0
	v_mfma_f32_16x16x32_bf16 v[96:99], v[174:177], v[190:193], 0
	v_mfma_f32_16x16x32_bf16 v[84:87], v[166:169], v[198:201], 0
	v_mfma_f32_16x16x32_bf16 v[80:83], v[174:177], v[198:201], 0
	v_mfma_f32_16x16x32_bf16 v[68:71], v[166:169], v[206:209], 0
	v_mfma_f32_16x16x32_bf16 v[64:67], v[174:177], v[206:209], 0
	v_mfma_f32_16x16x32_bf16 v[116:119], v[170:173], v[186:189], v[116:119]
	v_mfma_f32_16x16x32_bf16 v[112:115], v[178:181], v[186:189], v[112:115]
	v_mfma_f32_16x16x32_bf16 v[100:103], v[170:173], v[194:197], v[100:103]
	v_mfma_f32_16x16x32_bf16 v[96:99], v[178:181], v[194:197], v[96:99]
	v_mfma_f32_16x16x32_bf16 v[84:87], v[170:173], v[202:205], v[84:87]
	v_mfma_f32_16x16x32_bf16 v[80:83], v[178:181], v[202:205], v[80:83]
	v_mfma_f32_16x16x32_bf16 v[68:71], v[170:173], v[210:213], v[68:71]
	v_mfma_f32_16x16x32_bf16 v[64:67], v[178:181], v[210:213], v[64:67]
	s_setprio 0
	s_barrier
	s_add_i32 s51, s42, s30
	v_lshl_add_u64 v[214:215], s[26:27], 0, v[132:133]
	s_mov_b32 m0, s51
	ds_read_b128 v[182:185], v153 offset:16384
	ds_read_b128 v[186:189], v246 offset:16384
	ds_read_b128 v[190:193], v153 offset:18432
	ds_read_b128 v[194:197], v246 offset:18432
	ds_read_b128 v[198:201], v153 offset:20480
	ds_read_b128 v[202:205], v246 offset:20480
	ds_read_b128 v[206:209], v153 offset:22528
	ds_read_b128 v[210:213], v246 offset:22528
	global_load_lds_dwordx4 v[214:215], off
	s_add_i32 m0, s51, 0x2000
	s_add_u32 s52, s26, 0x40000
	v_lshl_add_u64 v[216:217], s[26:27], 0, v[128:129]
	s_addc_u32 s53, s27, 0
	s_add_i32 s51, s43, s30
	global_load_lds_dwordx4 v[216:217], off
	v_lshl_add_u64 v[218:219], s[52:53], 0, v[132:133]
	s_mov_b32 m0, s51
	v_lshl_add_u64 v[220:221], s[28:29], 0, v[130:131]
	global_load_lds_dwordx4 v[218:219], off
	v_lshl_add_u64 v[218:219], s[52:53], 0, v[128:129]
	s_add_i32 m0, s51, 0x2000
	s_nop 0
	global_load_lds_dwordx4 v[218:219], off
	v_lshl_add_u64 v[218:219], s[28:29], 0, v[134:135]
	s_mov_b32 m0, s23
	s_nop 0
	global_load_lds_dwordx4 v[218:219], off
	s_mov_b32 m0, s34
	s_nop 0
	global_load_lds_dwordx4 v[220:221], off
	s_waitcnt vmcnt(8)
	s_waitcnt lgkmcnt(0)
	s_barrier
	s_setprio 0
	s_waitcnt lgkmcnt(0)
	v_mfma_f32_16x16x32_bf16 v[60:63], v[144:147], v[182:185], 0
	v_mfma_f32_16x16x32_bf16 v[56:59], v[158:161], v[182:185], 0
	v_mfma_f32_16x16x32_bf16 v[44:47], v[144:147], v[190:193], 0
	v_mfma_f32_16x16x32_bf16 v[40:43], v[158:161], v[190:193], 0
	v_mfma_f32_16x16x32_bf16 v[28:31], v[144:147], v[198:201], 0
	v_mfma_f32_16x16x32_bf16 v[24:27], v[158:161], v[198:201], 0
	v_mfma_f32_16x16x32_bf16 v[12:15], v[144:147], v[206:209], 0
	v_mfma_f32_16x16x32_bf16 v[8:11], v[158:161], v[206:209], 0
	v_mfma_f32_16x16x32_bf16 v[60:63], v[154:157], v[186:189], v[60:63]
	v_mfma_f32_16x16x32_bf16 v[56:59], v[162:165], v[186:189], v[56:59]
	v_mfma_f32_16x16x32_bf16 v[44:47], v[154:157], v[194:197], v[44:47]
	v_mfma_f32_16x16x32_bf16 v[40:43], v[162:165], v[194:197], v[40:43]
	v_mfma_f32_16x16x32_bf16 v[28:31], v[154:157], v[202:205], v[28:31]
	v_mfma_f32_16x16x32_bf16 v[24:27], v[162:165], v[202:205], v[24:27]
	v_mfma_f32_16x16x32_bf16 v[12:15], v[154:157], v[210:213], v[12:15]
	v_mfma_f32_16x16x32_bf16 v[8:11], v[162:165], v[210:213], v[8:11]
	s_setprio 0
	s_setprio 0
	v_mfma_f32_16x16x32_bf16 v[52:55], v[166:169], v[182:185], 0
	v_mfma_f32_16x16x32_bf16 v[48:51], v[174:177], v[182:185], 0
	v_mfma_f32_16x16x32_bf16 v[36:39], v[166:169], v[190:193], 0
	v_mfma_f32_16x16x32_bf16 v[32:35], v[174:177], v[190:193], 0
	v_mfma_f32_16x16x32_bf16 v[20:23], v[166:169], v[198:201], 0
	v_mfma_f32_16x16x32_bf16 v[16:19], v[174:177], v[198:201], 0
	v_mfma_f32_16x16x32_bf16 v[4:7], v[166:169], v[206:209], 0
	v_mfma_f32_16x16x32_bf16 v[0:3], v[174:177], v[206:209], 0
	v_mfma_f32_16x16x32_bf16 v[52:55], v[170:173], v[186:189], v[52:55]
	v_mfma_f32_16x16x32_bf16 v[48:51], v[178:181], v[186:189], v[48:51]
	v_mfma_f32_16x16x32_bf16 v[36:39], v[170:173], v[194:197], v[36:39]
	v_mfma_f32_16x16x32_bf16 v[32:35], v[178:181], v[194:197], v[32:35]
	v_mfma_f32_16x16x32_bf16 v[20:23], v[170:173], v[202:205], v[20:23]
	v_mfma_f32_16x16x32_bf16 v[16:19], v[178:181], v[202:205], v[16:19]
	v_mfma_f32_16x16x32_bf16 v[4:7], v[170:173], v[210:213], v[4:7]
	v_mfma_f32_16x16x32_bf16 v[0:3], v[178:181], v[210:213], v[0:3]
	s_setprio 0
	s_barrier
	s_add_i32 s51, 0, 0x18000
	s_add_i32 s52, 0, 0x1c000
	v_add_u32_e32 v162, s51, v149
	v_add_u32_e32 v250, s51, v247
	v_add_u32_e32 v178, s52, v149
	v_add_u32_e32 v251, s52, v247
	ds_read_b128 v[144:147], v162
	ds_read_b128 v[154:157], v250
	ds_read_b128 v[158:161], v162 offset:2048
	ds_read_b128 v[162:165], v250 offset:2048
	ds_read_b128 v[166:169], v178
	ds_read_b128 v[170:173], v251
	ds_read_b128 v[174:177], v178 offset:2048
	ds_read_b128 v[178:181], v251 offset:2048
	s_add_u32 s28, s28, 0x40000
	s_addc_u32 s29, s29, 0
	s_mov_b32 m0, s35
	v_lshl_add_u64 v[222:223], s[28:29], 0, v[134:135]
	ds_read_b128 v[182:185], v153 offset:32768
	ds_read_b128 v[186:189], v246 offset:32768
	ds_read_b128 v[190:193], v153 offset:34816
	ds_read_b128 v[194:197], v246 offset:34816
	ds_read_b128 v[198:201], v153 offset:36864
	ds_read_b128 v[202:205], v246 offset:36864
	ds_read_b128 v[206:209], v153 offset:38912
	ds_read_b128 v[210:213], v246 offset:38912
	global_load_lds_dwordx4 v[222:223], off
	v_lshl_add_u64 v[222:223], s[28:29], 0, v[130:131]
	s_mov_b32 m0, s36
	s_nop 0
	global_load_lds_dwordx4 v[222:223], off
	s_waitcnt vmcnt(8)
	s_waitcnt lgkmcnt(0)
	s_barrier
	s_setprio 0
	s_waitcnt lgkmcnt(0)
	v_mfma_f32_16x16x32_bf16 v[124:127], v[144:147], v[182:185], v[124:127]
	v_mfma_f32_16x16x32_bf16 v[120:123], v[158:161], v[182:185], v[120:123]
	v_mfma_f32_16x16x32_bf16 v[108:111], v[144:147], v[190:193], v[108:111]
	v_mfma_f32_16x16x32_bf16 v[104:107], v[158:161], v[190:193], v[104:107]
	v_mfma_f32_16x16x32_bf16 v[92:95], v[144:147], v[198:201], v[92:95]
	v_mfma_f32_16x16x32_bf16 v[88:91], v[158:161], v[198:201], v[88:91]
	v_mfma_f32_16x16x32_bf16 v[76:79], v[144:147], v[206:209], v[76:79]
	v_mfma_f32_16x16x32_bf16 v[72:75], v[158:161], v[206:209], v[72:75]
	v_mfma_f32_16x16x32_bf16 v[124:127], v[154:157], v[186:189], v[124:127]
	v_mfma_f32_16x16x32_bf16 v[120:123], v[162:165], v[186:189], v[120:123]
	v_mfma_f32_16x16x32_bf16 v[108:111], v[154:157], v[194:197], v[108:111]
	v_mfma_f32_16x16x32_bf16 v[104:107], v[162:165], v[194:197], v[104:107]
	v_mfma_f32_16x16x32_bf16 v[92:95], v[154:157], v[202:205], v[92:95]
	v_mfma_f32_16x16x32_bf16 v[88:91], v[162:165], v[202:205], v[88:91]
	v_mfma_f32_16x16x32_bf16 v[76:79], v[154:157], v[210:213], v[76:79]
	v_mfma_f32_16x16x32_bf16 v[72:75], v[162:165], v[210:213], v[72:75]
	s_setprio 0
	s_setprio 0
	v_mfma_f32_16x16x32_bf16 v[116:119], v[166:169], v[182:185], v[116:119]
	v_mfma_f32_16x16x32_bf16 v[112:115], v[174:177], v[182:185], v[112:115]
	v_mfma_f32_16x16x32_bf16 v[100:103], v[166:169], v[190:193], v[100:103]
	v_mfma_f32_16x16x32_bf16 v[96:99], v[174:177], v[190:193], v[96:99]
	v_mfma_f32_16x16x32_bf16 v[84:87], v[166:169], v[198:201], v[84:87]
	v_mfma_f32_16x16x32_bf16 v[80:83], v[174:177], v[198:201], v[80:83]
	v_mfma_f32_16x16x32_bf16 v[68:71], v[166:169], v[206:209], v[68:71]
	v_mfma_f32_16x16x32_bf16 v[64:67], v[174:177], v[206:209], v[64:67]
	v_mfma_f32_16x16x32_bf16 v[116:119], v[170:173], v[186:189], v[116:119]
	v_mfma_f32_16x16x32_bf16 v[112:115], v[178:181], v[186:189], v[112:115]
	v_mfma_f32_16x16x32_bf16 v[100:103], v[170:173], v[194:197], v[100:103]
	v_mfma_f32_16x16x32_bf16 v[96:99], v[178:181], v[194:197], v[96:99]
	v_mfma_f32_16x16x32_bf16 v[84:87], v[170:173], v[202:205], v[84:87]
	v_mfma_f32_16x16x32_bf16 v[80:83], v[178:181], v[202:205], v[80:83]
	v_mfma_f32_16x16x32_bf16 v[68:71], v[170:173], v[210:213], v[68:71]
	v_mfma_f32_16x16x32_bf16 v[64:67], v[178:181], v[210:213], v[64:67]
	s_setprio 0
	s_barrier
	s_add_i32 s28, s51, s30
	v_lshl_add_u64 v[214:215], v[214:215], 0, s[10:11]
	s_mov_b32 m0, s28
	ds_read_b128 v[182:185], v153 offset:49152
	ds_read_b128 v[186:189], v246 offset:49152
	ds_read_b128 v[190:193], v153 offset:51200
	ds_read_b128 v[194:197], v246 offset:51200
	ds_read_b128 v[198:201], v153 offset:53248
	ds_read_b128 v[202:205], v246 offset:53248
	ds_read_b128 v[206:209], v153 offset:55296
	ds_read_b128 v[210:213], v246 offset:55296
	global_load_lds_dwordx4 v[214:215], off
	s_add_i32 m0, s28, 0x2000
	s_add_u32 s26, s26, 0x40080
	v_lshl_add_u64 v[214:215], v[216:217], 0, s[10:11]
	s_addc_u32 s27, s27, 0
	s_add_i32 s28, s52, s30
	global_load_lds_dwordx4 v[214:215], off
	v_lshl_add_u64 v[214:215], s[26:27], 0, v[132:133]
	s_mov_b32 m0, s28
	s_nop 0
	global_load_lds_dwordx4 v[214:215], off
	v_lshl_add_u64 v[214:215], s[26:27], 0, v[128:129]
	s_add_i32 m0, s28, 0x2000
	s_nop 0
	global_load_lds_dwordx4 v[214:215], off
	v_lshl_add_u64 v[214:215], v[218:219], 0, s[10:11]
	s_mov_b32 m0, s39
	s_nop 0
	global_load_lds_dwordx4 v[214:215], off
	v_lshl_add_u64 v[214:215], v[220:221], 0, s[10:11]
	s_mov_b32 m0, s40
	s_nop 0
	global_load_lds_dwordx4 v[214:215], off
	s_waitcnt vmcnt(8)
	s_waitcnt lgkmcnt(0)
	s_barrier
	s_setprio 0
	s_waitcnt lgkmcnt(0)
	v_mfma_f32_16x16x32_bf16 v[60:63], v[144:147], v[182:185], v[60:63]
	v_mfma_f32_16x16x32_bf16 v[56:59], v[158:161], v[182:185], v[56:59]
	v_mfma_f32_16x16x32_bf16 v[44:47], v[144:147], v[190:193], v[44:47]
	v_mfma_f32_16x16x32_bf16 v[40:43], v[158:161], v[190:193], v[40:43]
	v_mfma_f32_16x16x32_bf16 v[28:31], v[144:147], v[198:201], v[28:31]
	v_mfma_f32_16x16x32_bf16 v[24:27], v[158:161], v[198:201], v[24:27]
	v_mfma_f32_16x16x32_bf16 v[12:15], v[144:147], v[206:209], v[12:15]
	v_mfma_f32_16x16x32_bf16 v[8:11], v[158:161], v[206:209], v[8:11]
	v_mfma_f32_16x16x32_bf16 v[60:63], v[154:157], v[186:189], v[60:63]
	v_mfma_f32_16x16x32_bf16 v[56:59], v[162:165], v[186:189], v[56:59]
	v_mfma_f32_16x16x32_bf16 v[44:47], v[154:157], v[194:197], v[44:47]
	v_mfma_f32_16x16x32_bf16 v[40:43], v[162:165], v[194:197], v[40:43]
	v_mfma_f32_16x16x32_bf16 v[28:31], v[154:157], v[202:205], v[28:31]
	v_mfma_f32_16x16x32_bf16 v[24:27], v[162:165], v[202:205], v[24:27]
	v_mfma_f32_16x16x32_bf16 v[12:15], v[154:157], v[210:213], v[12:15]
	v_mfma_f32_16x16x32_bf16 v[8:11], v[162:165], v[210:213], v[8:11]
	s_setprio 0
	s_setprio 0
	v_mfma_f32_16x16x32_bf16 v[52:55], v[166:169], v[182:185], v[52:55]
	v_mfma_f32_16x16x32_bf16 v[48:51], v[174:177], v[182:185], v[48:51]
	v_mfma_f32_16x16x32_bf16 v[36:39], v[166:169], v[190:193], v[36:39]
	v_mfma_f32_16x16x32_bf16 v[32:35], v[174:177], v[190:193], v[32:35]
	v_mfma_f32_16x16x32_bf16 v[20:23], v[166:169], v[198:201], v[20:23]
	v_mfma_f32_16x16x32_bf16 v[16:19], v[174:177], v[198:201], v[16:19]
	v_mfma_f32_16x16x32_bf16 v[4:7], v[166:169], v[206:209], v[4:7]
	v_mfma_f32_16x16x32_bf16 v[0:3], v[174:177], v[206:209], v[0:3]
	v_mfma_f32_16x16x32_bf16 v[52:55], v[170:173], v[186:189], v[52:55]
	v_mfma_f32_16x16x32_bf16 v[48:51], v[178:181], v[186:189], v[48:51]
	v_mfma_f32_16x16x32_bf16 v[36:39], v[170:173], v[194:197], v[36:39]
	v_mfma_f32_16x16x32_bf16 v[32:35], v[178:181], v[194:197], v[32:35]
	v_mfma_f32_16x16x32_bf16 v[20:23], v[170:173], v[202:205], v[20:23]
	v_mfma_f32_16x16x32_bf16 v[16:19], v[178:181], v[202:205], v[16:19]
	v_mfma_f32_16x16x32_bf16 v[4:7], v[170:173], v[210:213], v[4:7]
	v_mfma_f32_16x16x32_bf16 v[0:3], v[178:181], v[210:213], v[0:3]
	s_setprio 0
	s_barrier
	s_add_i32 s50, s50, 2
	s_add_u32 s24, s24, 0x100
	s_addc_u32 s25, s25, 0
	s_add_u32 s48, s48, 0x100
	s_addc_u32 s49, s49, 0
	s_cmp_gt_u32 s50, 13

.LBB0_295:
	s_add_u32 s46, s20, 0x100
	s_addc_u32 s47, s21, 0
	s_mov_b32 s48, -2
	s_waitcnt lgkmcnt(0)
	v_xor_b32_e32 v246, 64, v171
	v_xor_b32_e32 v247, 64, v167
	v_add_u32_e32 v248, s40, v247
	v_add_u32_e32 v249, s41, v247
	ds_read_b128 v[144:147], v169
	ds_read_b128 v[148:151], v248
	ds_read_b128 v[152:155], v169 offset:2048
	ds_read_b128 v[156:159], v248 offset:2048
	ds_read_b128 v[160:163], v170
	ds_read_b128 v[172:175], v249
	ds_read_b128 v[176:179], v170 offset:2048
	ds_read_b128 v[180:183], v249 offset:2048
	s_add_u32 s20, s18, 0x100
	s_addc_u32 s21, s19, 0
	s_cmp_eq_u32 s48, 40
	s_cselect_b32 s25, s9, s21
	s_cselect_b32 s24, s8, s20
	s_cselect_b32 s23, s17, s47
	s_cselect_b32 s22, s16, s46
	v_lshl_add_u64 v[164:165], s[18:19], 0, v[136:137]
	s_add_i32 m0, s28, 0xc000
	ds_read_b128 v[184:187], v171
	ds_read_b128 v[188:191], v246
	ds_read_b128 v[192:195], v171 offset:2048
	ds_read_b128 v[196:199], v246 offset:2048
	ds_read_b128 v[200:203], v171 offset:4096
	ds_read_b128 v[204:207], v246 offset:4096
	ds_read_b128 v[208:211], v171 offset:6144
	ds_read_b128 v[212:215], v246 offset:6144
	global_load_lds_dwordx4 v[164:165], off
	v_lshl_add_u64 v[164:165], s[18:19], 0, v[138:139]
	s_add_i32 m0, s28, 0xe000
	s_nop 0
	global_load_lds_dwordx4 v[164:165], off
	s_waitcnt vmcnt(8)
	s_waitcnt lgkmcnt(0)
	s_barrier
	s_setprio 0
	s_waitcnt lgkmcnt(0)
	v_mfma_f32_16x16x32_bf16 v[124:127], v[144:147], v[184:187], 0
	v_mfma_f32_16x16x32_bf16 v[120:123], v[152:155], v[184:187], 0
	v_mfma_f32_16x16x32_bf16 v[116:119], v[144:147], v[192:195], 0
	v_mfma_f32_16x16x32_bf16 v[112:115], v[152:155], v[192:195], 0
	v_mfma_f32_16x16x32_bf16 v[96:99], v[144:147], v[200:203], 0
	v_mfma_f32_16x16x32_bf16 v[88:91], v[152:155], v[200:203], 0
	v_mfma_f32_16x16x32_bf16 v[80:83], v[144:147], v[208:211], 0
	v_mfma_f32_16x16x32_bf16 v[72:75], v[152:155], v[208:211], 0
	v_mfma_f32_16x16x32_bf16 v[124:127], v[148:151], v[188:191], v[124:127]
	v_mfma_f32_16x16x32_bf16 v[120:123], v[156:159], v[188:191], v[120:123]
	v_mfma_f32_16x16x32_bf16 v[116:119], v[148:151], v[196:199], v[116:119]
	v_mfma_f32_16x16x32_bf16 v[112:115], v[156:159], v[196:199], v[112:115]
	v_mfma_f32_16x16x32_bf16 v[96:99], v[148:151], v[204:207], v[96:99]
	v_mfma_f32_16x16x32_bf16 v[88:91], v[156:159], v[204:207], v[88:91]
	v_mfma_f32_16x16x32_bf16 v[80:83], v[148:151], v[212:215], v[80:83]
	v_mfma_f32_16x16x32_bf16 v[72:75], v[156:159], v[212:215], v[72:75]
	s_setprio 0
	s_setprio 0
	v_mfma_f32_16x16x32_bf16 v[108:111], v[160:163], v[184:187], 0
	v_mfma_f32_16x16x32_bf16 v[104:107], v[176:179], v[184:187], 0
	v_mfma_f32_16x16x32_bf16 v[100:103], v[160:163], v[192:195], 0
	v_mfma_f32_16x16x32_bf16 v[92:95], v[176:179], v[192:195], 0
	v_mfma_f32_16x16x32_bf16 v[84:87], v[160:163], v[200:203], 0
	v_mfma_f32_16x16x32_bf16 v[76:79], v[176:179], v[200:203], 0
	v_mfma_f32_16x16x32_bf16 v[68:71], v[160:163], v[208:211], 0
	v_mfma_f32_16x16x32_bf16 v[64:67], v[176:179], v[208:211], 0
	v_mfma_f32_16x16x32_bf16 v[108:111], v[172:175], v[188:191], v[108:111]
	v_mfma_f32_16x16x32_bf16 v[104:107], v[180:183], v[188:191], v[104:107]
	v_mfma_f32_16x16x32_bf16 v[100:103], v[172:175], v[196:199], v[100:103]
	v_mfma_f32_16x16x32_bf16 v[92:95], v[180:183], v[196:199], v[92:95]
	v_mfma_f32_16x16x32_bf16 v[84:87], v[172:175], v[204:207], v[84:87]
	v_mfma_f32_16x16x32_bf16 v[76:79], v[180:183], v[204:207], v[76:79]
	v_mfma_f32_16x16x32_bf16 v[68:71], v[172:175], v[212:215], v[68:71]
	v_mfma_f32_16x16x32_bf16 v[64:67], v[180:183], v[212:215], v[64:67]
	s_setprio 0
	s_barrier
	s_add_i32 s18, s40, s26
	v_lshl_add_u64 v[164:165], s[22:23], 0, v[132:133]
	s_mov_b32 m0, s18
	ds_read_b128 v[184:187], v171 offset:16384
	ds_read_b128 v[188:191], v246 offset:16384
	ds_read_b128 v[192:195], v171 offset:18432
	ds_read_b128 v[196:199], v246 offset:18432
	ds_read_b128 v[200:203], v171 offset:20480
	ds_read_b128 v[204:207], v246 offset:20480
	ds_read_b128 v[208:211], v171 offset:22528
	ds_read_b128 v[212:215], v246 offset:22528
	global_load_lds_dwordx4 v[164:165], off
	s_add_i32 m0, s18, 0x2000
	s_add_u32 s18, s22, 0xb0000
	v_lshl_add_u64 v[216:217], s[22:23], 0, v[128:129]
	s_addc_u32 s19, s23, 0
	s_add_i32 s49, s41, s26
	global_load_lds_dwordx4 v[216:217], off
	v_lshl_add_u64 v[218:219], s[18:19], 0, v[132:133]
	s_mov_b32 m0, s49
	v_lshl_add_u64 v[220:221], s[24:25], 0, v[130:131]
	global_load_lds_dwordx4 v[218:219], off
	v_lshl_add_u64 v[218:219], s[18:19], 0, v[128:129]
	s_add_i32 m0, s49, 0x2000
	s_nop 0
	global_load_lds_dwordx4 v[218:219], off
	v_lshl_add_u64 v[218:219], s[24:25], 0, v[134:135]
	s_mov_b32 m0, s28
	s_nop 0
	global_load_lds_dwordx4 v[218:219], off
	s_mov_b32 m0, s29
	s_nop 0
	global_load_lds_dwordx4 v[220:221], off
	s_waitcnt vmcnt(8)
	s_waitcnt lgkmcnt(0)
	s_barrier
	s_setprio 0
	s_waitcnt lgkmcnt(0)
	v_mfma_f32_16x16x32_bf16 v[60:63], v[144:147], v[184:187], 0
	v_mfma_f32_16x16x32_bf16 v[56:59], v[152:155], v[184:187], 0
	v_mfma_f32_16x16x32_bf16 v[48:51], v[144:147], v[192:195], 0
	v_mfma_f32_16x16x32_bf16 v[40:43], v[152:155], v[192:195], 0
	v_mfma_f32_16x16x32_bf16 v[32:35], v[144:147], v[200:203], 0
	v_mfma_f32_16x16x32_bf16 v[24:27], v[152:155], v[200:203], 0
	v_mfma_f32_16x16x32_bf16 v[16:19], v[144:147], v[208:211], 0
	v_mfma_f32_16x16x32_bf16 v[8:11], v[152:155], v[208:211], 0
	v_mfma_f32_16x16x32_bf16 v[60:63], v[148:151], v[188:191], v[60:63]
	v_mfma_f32_16x16x32_bf16 v[56:59], v[156:159], v[188:191], v[56:59]
	v_mfma_f32_16x16x32_bf16 v[48:51], v[148:151], v[196:199], v[48:51]
	v_mfma_f32_16x16x32_bf16 v[40:43], v[156:159], v[196:199], v[40:43]
	v_mfma_f32_16x16x32_bf16 v[32:35], v[148:151], v[204:207], v[32:35]
	v_mfma_f32_16x16x32_bf16 v[24:27], v[156:159], v[204:207], v[24:27]
	v_mfma_f32_16x16x32_bf16 v[16:19], v[148:151], v[212:215], v[16:19]
	v_mfma_f32_16x16x32_bf16 v[8:11], v[156:159], v[212:215], v[8:11]
	s_setprio 0
	s_setprio 0
	v_mfma_f32_16x16x32_bf16 v[52:55], v[160:163], v[184:187], 0
	v_mfma_f32_16x16x32_bf16 v[44:47], v[176:179], v[184:187], 0
	v_mfma_f32_16x16x32_bf16 v[36:39], v[160:163], v[192:195], 0
	v_mfma_f32_16x16x32_bf16 v[28:31], v[176:179], v[192:195], 0
	v_mfma_f32_16x16x32_bf16 v[20:23], v[160:163], v[200:203], 0
	v_mfma_f32_16x16x32_bf16 v[12:15], v[176:179], v[200:203], 0
	v_mfma_f32_16x16x32_bf16 v[4:7], v[160:163], v[208:211], 0
	v_mfma_f32_16x16x32_bf16 v[0:3], v[176:179], v[208:211], 0
	v_mfma_f32_16x16x32_bf16 v[52:55], v[172:175], v[188:191], v[52:55]
	v_mfma_f32_16x16x32_bf16 v[44:47], v[180:183], v[188:191], v[44:47]
	v_mfma_f32_16x16x32_bf16 v[36:39], v[172:175], v[196:199], v[36:39]
	v_mfma_f32_16x16x32_bf16 v[28:31], v[180:183], v[196:199], v[28:31]
	v_mfma_f32_16x16x32_bf16 v[20:23], v[172:175], v[204:207], v[20:23]
	v_mfma_f32_16x16x32_bf16 v[12:15], v[180:183], v[204:207], v[12:15]
	v_mfma_f32_16x16x32_bf16 v[4:7], v[172:175], v[212:215], v[4:7]
	v_mfma_f32_16x16x32_bf16 v[0:3], v[180:183], v[212:215], v[0:3]
	s_setprio 0
	s_barrier
	s_add_i32 s49, 0, 0x18000
	s_add_i32 s50, 0, 0x1c000
	v_add_u32_e32 v156, s49, v167
	v_add_u32_e32 v250, s49, v247
	v_add_u32_e32 v180, s50, v167
	v_add_u32_e32 v251, s50, v247
	ds_read_b128 v[144:147], v156
	ds_read_b128 v[148:151], v250
	ds_read_b128 v[152:155], v156 offset:2048
	ds_read_b128 v[156:159], v250 offset:2048
	ds_read_b128 v[160:163], v180
	ds_read_b128 v[172:175], v251
	ds_read_b128 v[176:179], v180 offset:2048
	ds_read_b128 v[180:183], v251 offset:2048
	s_add_u32 s18, s24, 0xb0000
	s_addc_u32 s19, s25, 0
	s_mov_b32 m0, s30
	v_lshl_add_u64 v[222:223], s[18:19], 0, v[134:135]
	ds_read_b128 v[184:187], v171 offset:32768
	ds_read_b128 v[188:191], v246 offset:32768
	ds_read_b128 v[192:195], v171 offset:34816
	ds_read_b128 v[196:199], v246 offset:34816
	ds_read_b128 v[200:203], v171 offset:36864
	ds_read_b128 v[204:207], v246 offset:36864
	ds_read_b128 v[208:211], v171 offset:38912
	ds_read_b128 v[212:215], v246 offset:38912
	global_load_lds_dwordx4 v[222:223], off
	v_lshl_add_u64 v[222:223], s[18:19], 0, v[130:131]
	s_mov_b32 m0, s31
	s_nop 0
	global_load_lds_dwordx4 v[222:223], off
	s_waitcnt vmcnt(8)
	s_waitcnt lgkmcnt(0)
	s_barrier
	s_setprio 0
	s_waitcnt lgkmcnt(0)
	v_mfma_f32_16x16x32_bf16 v[124:127], v[144:147], v[184:187], v[124:127]
	v_mfma_f32_16x16x32_bf16 v[120:123], v[152:155], v[184:187], v[120:123]
	v_mfma_f32_16x16x32_bf16 v[116:119], v[144:147], v[192:195], v[116:119]
	v_mfma_f32_16x16x32_bf16 v[112:115], v[152:155], v[192:195], v[112:115]
	v_mfma_f32_16x16x32_bf16 v[96:99], v[144:147], v[200:203], v[96:99]
	v_mfma_f32_16x16x32_bf16 v[88:91], v[152:155], v[200:203], v[88:91]
	v_mfma_f32_16x16x32_bf16 v[80:83], v[144:147], v[208:211], v[80:83]
	v_mfma_f32_16x16x32_bf16 v[72:75], v[152:155], v[208:211], v[72:75]
	v_mfma_f32_16x16x32_bf16 v[124:127], v[148:151], v[188:191], v[124:127]
	v_mfma_f32_16x16x32_bf16 v[120:123], v[156:159], v[188:191], v[120:123]
	v_mfma_f32_16x16x32_bf16 v[116:119], v[148:151], v[196:199], v[116:119]
	v_mfma_f32_16x16x32_bf16 v[112:115], v[156:159], v[196:199], v[112:115]
	v_mfma_f32_16x16x32_bf16 v[96:99], v[148:151], v[204:207], v[96:99]
	v_mfma_f32_16x16x32_bf16 v[88:91], v[156:159], v[204:207], v[88:91]
	v_mfma_f32_16x16x32_bf16 v[80:83], v[148:151], v[212:215], v[80:83]
	v_mfma_f32_16x16x32_bf16 v[72:75], v[156:159], v[212:215], v[72:75]
	s_setprio 0
	s_setprio 0
	v_mfma_f32_16x16x32_bf16 v[108:111], v[160:163], v[184:187], v[108:111]
	v_mfma_f32_16x16x32_bf16 v[104:107], v[176:179], v[184:187], v[104:107]
	v_mfma_f32_16x16x32_bf16 v[100:103], v[160:163], v[192:195], v[100:103]
	v_mfma_f32_16x16x32_bf16 v[92:95], v[176:179], v[192:195], v[92:95]
	v_mfma_f32_16x16x32_bf16 v[84:87], v[160:163], v[200:203], v[84:87]
	v_mfma_f32_16x16x32_bf16 v[76:79], v[176:179], v[200:203], v[76:79]
	v_mfma_f32_16x16x32_bf16 v[68:71], v[160:163], v[208:211], v[68:71]
	v_mfma_f32_16x16x32_bf16 v[64:67], v[176:179], v[208:211], v[64:67]
	v_mfma_f32_16x16x32_bf16 v[108:111], v[172:175], v[188:191], v[108:111]
	v_mfma_f32_16x16x32_bf16 v[104:107], v[180:183], v[188:191], v[104:107]
	v_mfma_f32_16x16x32_bf16 v[100:103], v[172:175], v[196:199], v[100:103]
	v_mfma_f32_16x16x32_bf16 v[92:95], v[180:183], v[196:199], v[92:95]
	v_mfma_f32_16x16x32_bf16 v[84:87], v[172:175], v[204:207], v[84:87]
	v_mfma_f32_16x16x32_bf16 v[76:79], v[180:183], v[204:207], v[76:79]
	v_mfma_f32_16x16x32_bf16 v[68:71], v[172:175], v[212:215], v[68:71]
	v_mfma_f32_16x16x32_bf16 v[64:67], v[180:183], v[212:215], v[64:67]
	s_setprio 0
	s_barrier
	s_add_i32 s18, s49, s26
	v_lshl_add_u64 v[164:165], v[164:165], 0, s[12:13]
	s_mov_b32 m0, s18
	ds_read_b128 v[184:187], v171 offset:49152
	ds_read_b128 v[188:191], v246 offset:49152
	ds_read_b128 v[192:195], v171 offset:51200
	ds_read_b128 v[196:199], v246 offset:51200
	ds_read_b128 v[200:203], v171 offset:53248
	ds_read_b128 v[204:207], v246 offset:53248
	ds_read_b128 v[208:211], v171 offset:55296
	ds_read_b128 v[212:215], v246 offset:55296
	global_load_lds_dwordx4 v[164:165], off
	s_add_i32 m0, s18, 0x2000
	s_add_u32 s18, s22, 0xb0080
	v_lshl_add_u64 v[164:165], v[216:217], 0, s[12:13]
	s_addc_u32 s19, s23, 0
	s_add_i32 s22, s50, s26
	global_load_lds_dwordx4 v[164:165], off
	v_lshl_add_u64 v[164:165], s[18:19], 0, v[132:133]
	s_mov_b32 m0, s22
	s_nop 0
	global_load_lds_dwordx4 v[164:165], off
	v_lshl_add_u64 v[164:165], s[18:19], 0, v[128:129]
	s_add_i32 m0, s22, 0x2000
	s_nop 0
	global_load_lds_dwordx4 v[164:165], off
	v_lshl_add_u64 v[164:165], v[218:219], 0, s[12:13]
	s_mov_b32 m0, s37
	s_nop 0
	global_load_lds_dwordx4 v[164:165], off
	v_lshl_add_u64 v[164:165], v[220:221], 0, s[12:13]
	s_mov_b32 m0, s38
	s_nop 0
	global_load_lds_dwordx4 v[164:165], off
	s_waitcnt vmcnt(8)
	s_waitcnt lgkmcnt(0)
	s_barrier
	s_setprio 0
	s_waitcnt lgkmcnt(0)
	v_mfma_f32_16x16x32_bf16 v[60:63], v[144:147], v[184:187], v[60:63]
	v_mfma_f32_16x16x32_bf16 v[56:59], v[152:155], v[184:187], v[56:59]
	v_mfma_f32_16x16x32_bf16 v[48:51], v[144:147], v[192:195], v[48:51]
	v_mfma_f32_16x16x32_bf16 v[40:43], v[152:155], v[192:195], v[40:43]
	v_mfma_f32_16x16x32_bf16 v[32:35], v[144:147], v[200:203], v[32:35]
	v_mfma_f32_16x16x32_bf16 v[24:27], v[152:155], v[200:203], v[24:27]
	v_mfma_f32_16x16x32_bf16 v[16:19], v[144:147], v[208:211], v[16:19]
	v_mfma_f32_16x16x32_bf16 v[8:11], v[152:155], v[208:211], v[8:11]
	v_mfma_f32_16x16x32_bf16 v[60:63], v[148:151], v[188:191], v[60:63]
	v_mfma_f32_16x16x32_bf16 v[56:59], v[156:159], v[188:191], v[56:59]
	v_mfma_f32_16x16x32_bf16 v[48:51], v[148:151], v[196:199], v[48:51]
	v_mfma_f32_16x16x32_bf16 v[40:43], v[156:159], v[196:199], v[40:43]
	v_mfma_f32_16x16x32_bf16 v[32:35], v[148:151], v[204:207], v[32:35]
	v_mfma_f32_16x16x32_bf16 v[24:27], v[156:159], v[204:207], v[24:27]
	v_mfma_f32_16x16x32_bf16 v[16:19], v[148:151], v[212:215], v[16:19]
	v_mfma_f32_16x16x32_bf16 v[8:11], v[156:159], v[212:215], v[8:11]
	s_setprio 0
	s_setprio 0
	v_mfma_f32_16x16x32_bf16 v[52:55], v[160:163], v[184:187], v[52:55]
	v_mfma_f32_16x16x32_bf16 v[44:47], v[176:179], v[184:187], v[44:47]
	v_mfma_f32_16x16x32_bf16 v[36:39], v[160:163], v[192:195], v[36:39]
	v_mfma_f32_16x16x32_bf16 v[28:31], v[176:179], v[192:195], v[28:31]
	v_mfma_f32_16x16x32_bf16 v[20:23], v[160:163], v[200:203], v[20:23]
	v_mfma_f32_16x16x32_bf16 v[12:15], v[176:179], v[200:203], v[12:15]
	v_mfma_f32_16x16x32_bf16 v[4:7], v[160:163], v[208:211], v[4:7]
	v_mfma_f32_16x16x32_bf16 v[0:3], v[176:179], v[208:211], v[0:3]
	v_mfma_f32_16x16x32_bf16 v[52:55], v[172:175], v[188:191], v[52:55]
	v_mfma_f32_16x16x32_bf16 v[44:47], v[180:183], v[188:191], v[44:47]
	v_mfma_f32_16x16x32_bf16 v[36:39], v[172:175], v[196:199], v[36:39]
	v_mfma_f32_16x16x32_bf16 v[28:31], v[180:183], v[196:199], v[28:31]
	v_mfma_f32_16x16x32_bf16 v[20:23], v[172:175], v[204:207], v[20:23]
	v_mfma_f32_16x16x32_bf16 v[12:15], v[180:183], v[204:207], v[12:15]
	v_mfma_f32_16x16x32_bf16 v[4:7], v[172:175], v[212:215], v[4:7]
	v_mfma_f32_16x16x32_bf16 v[0:3], v[180:183], v[212:215], v[0:3]
	s_setprio 0
	s_barrier
	s_add_i32 s48, s48, 2
	s_add_u32 s46, s46, 0x100
	s_addc_u32 s47, s47, 0
	s_cmp_gt_u32 s48, 41
	s_mov_b64 s[18:19], s[20:21]

.LBB0_432:
	s_ashr_i32 s23, s22, 31
	s_lshl_b64 s[24:25], s[22:23], 19
	s_add_u32 s24, s90, s24
	s_addc_u32 s25, s91, s25
	s_and_b64 s[26:27], s[6:7], exec
	s_cselect_b32 s9, s25, s29
	s_cselect_b32 s23, s24, s28
	s_ashr_i32 s21, s20, 31
	s_lshl_b64 s[26:27], s[20:21], 19
	s_add_u32 s26, s2, s26
	s_addc_u32 s27, s3, s27
	s_and_b64 s[34:35], s[6:7], exec
	s_cselect_b32 s21, s27, s31
	s_cselect_b32 s55, s26, s30
	s_add_u32 s28, s28, 0x40080
	s_addc_u32 s29, s29, 0
	s_add_u32 s56, s30, 0x100
	s_addc_u32 s57, s31, 0
	s_mov_b32 s58, -2
	v_xor_b32_e32 v246, 64, v241
	v_xor_b32_e32 v247, 64, v237
	v_add_u32_e32 v248, s50, v247
	v_add_u32_e32 v249, s51, v247
	ds_read_b128 v[130:133], v239
	ds_read_b128 v[134:137], v248
	ds_read_b128 v[138:141], v239 offset:2048
	ds_read_b128 v[142:145], v248 offset:2048
	ds_read_b128 v[146:149], v240
	ds_read_b128 v[150:153], v249
	ds_read_b128 v[154:157], v240 offset:2048
	ds_read_b128 v[158:161], v249 offset:2048
	s_add_u32 s30, s28, 0xfffc0080
	s_addc_u32 s31, s29, -1
	s_cmp_eq_u32 s58, 12
	s_cselect_b32 s35, s9, s31
	s_cselect_b32 s34, s23, s30
	s_cselect_b32 s31, s21, s57
	s_cselect_b32 s30, s55, s56
	v_lshl_add_u64 v[80:81], s[28:29], 0, v[222:223]
	s_add_i32 m0, s36, 0xc000
	ds_read_b128 v[162:165], v241
	ds_read_b128 v[166:169], v246
	ds_read_b128 v[170:173], v241 offset:2048
	ds_read_b128 v[174:177], v246 offset:2048
	ds_read_b128 v[178:181], v241 offset:4096
	ds_read_b128 v[182:185], v246 offset:4096
	ds_read_b128 v[186:189], v241 offset:6144
	ds_read_b128 v[190:193], v246 offset:6144
	global_load_lds_dwordx4 v[80:81], off
	v_lshl_add_u64 v[80:81], s[28:29], 0, v[224:225]
	s_add_i32 m0, s36, 0xe000
	s_nop 0
	global_load_lds_dwordx4 v[80:81], off
	s_waitcnt vmcnt(8)
	s_waitcnt lgkmcnt(0)
	s_barrier
	s_setprio 0
	s_waitcnt lgkmcnt(0)
	v_mfma_f32_16x16x32_bf16 v[126:129], v[130:133], v[162:165], 0
	v_mfma_f32_16x16x32_bf16 v[122:125], v[138:141], v[162:165], 0
	v_mfma_f32_16x16x32_bf16 v[110:113], v[130:133], v[170:173], 0
	v_mfma_f32_16x16x32_bf16 v[106:109], v[138:141], v[170:173], 0
	v_mfma_f32_16x16x32_bf16 v[94:97], v[130:133], v[178:181], 0
	v_mfma_f32_16x16x32_bf16 v[90:93], v[138:141], v[178:181], 0
	v_mfma_f32_16x16x32_bf16 v[76:79], v[130:133], v[186:189], 0
	v_mfma_f32_16x16x32_bf16 v[72:75], v[138:141], v[186:189], 0
	v_mfma_f32_16x16x32_bf16 v[126:129], v[134:137], v[166:169], v[126:129]
	v_mfma_f32_16x16x32_bf16 v[122:125], v[142:145], v[166:169], v[122:125]
	v_mfma_f32_16x16x32_bf16 v[110:113], v[134:137], v[174:177], v[110:113]
	v_mfma_f32_16x16x32_bf16 v[106:109], v[142:145], v[174:177], v[106:109]
	v_mfma_f32_16x16x32_bf16 v[94:97], v[134:137], v[182:185], v[94:97]
	v_mfma_f32_16x16x32_bf16 v[90:93], v[142:145], v[182:185], v[90:93]
	v_mfma_f32_16x16x32_bf16 v[76:79], v[134:137], v[190:193], v[76:79]
	v_mfma_f32_16x16x32_bf16 v[72:75], v[142:145], v[190:193], v[72:75]
	s_setprio 0
	s_setprio 0
	v_mfma_f32_16x16x32_bf16 v[118:121], v[146:149], v[162:165], 0
	v_mfma_f32_16x16x32_bf16 v[114:117], v[154:157], v[162:165], 0
	v_mfma_f32_16x16x32_bf16 v[102:105], v[146:149], v[170:173], 0
	v_mfma_f32_16x16x32_bf16 v[98:101], v[154:157], v[170:173], 0
	v_mfma_f32_16x16x32_bf16 v[86:89], v[146:149], v[178:181], 0
	v_mfma_f32_16x16x32_bf16 v[80:83], v[154:157], v[178:181], 0
	v_mfma_f32_16x16x32_bf16 v[68:71], v[146:149], v[186:189], 0
	v_mfma_f32_16x16x32_bf16 v[64:67], v[154:157], v[186:189], 0
	v_mfma_f32_16x16x32_bf16 v[118:121], v[150:153], v[166:169], v[118:121]
	v_mfma_f32_16x16x32_bf16 v[114:117], v[158:161], v[166:169], v[114:117]
	v_mfma_f32_16x16x32_bf16 v[102:105], v[150:153], v[174:177], v[102:105]
	v_mfma_f32_16x16x32_bf16 v[98:101], v[158:161], v[174:177], v[98:101]
	v_mfma_f32_16x16x32_bf16 v[86:89], v[150:153], v[182:185], v[86:89]
	v_mfma_f32_16x16x32_bf16 v[80:83], v[158:161], v[182:185], v[80:83]
	v_mfma_f32_16x16x32_bf16 v[68:71], v[150:153], v[190:193], v[68:71]
	v_mfma_f32_16x16x32_bf16 v[64:67], v[158:161], v[190:193], v[64:67]
	s_setprio 0
	s_barrier
	s_add_i32 s59, s50, s33
	v_lshl_add_u64 v[194:195], s[30:31], 0, v[212:213]
	s_mov_b32 m0, s59
	ds_read_b128 v[162:165], v241 offset:16384
	ds_read_b128 v[166:169], v246 offset:16384
	ds_read_b128 v[170:173], v241 offset:18432
	ds_read_b128 v[174:177], v246 offset:18432
	ds_read_b128 v[178:181], v241 offset:20480
	ds_read_b128 v[182:185], v246 offset:20480
	ds_read_b128 v[186:189], v241 offset:22528
	ds_read_b128 v[190:193], v246 offset:22528
	global_load_lds_dwordx4 v[194:195], off
	s_add_i32 m0, s59, 0x2000
	s_add_u32 s60, s30, 0x40000
	v_lshl_add_u64 v[196:197], s[30:31], 0, v[216:217]
	s_addc_u32 s61, s31, 0
	s_add_i32 s59, s51, s33
	global_load_lds_dwordx4 v[196:197], off
	v_lshl_add_u64 v[84:85], s[60:61], 0, v[212:213]
	s_mov_b32 m0, s59
	v_lshl_add_u64 v[198:199], s[34:35], 0, v[210:211]
	global_load_lds_dwordx4 v[84:85], off
	v_lshl_add_u64 v[84:85], s[60:61], 0, v[216:217]
	s_add_i32 m0, s59, 0x2000
	v_lshl_add_u64 v[200:201], s[34:35], 0, v[214:215]
	global_load_lds_dwordx4 v[84:85], off
	s_mov_b32 m0, s36
	s_nop 0
	global_load_lds_dwordx4 v[198:199], off
	s_mov_b32 m0, s37
	s_nop 0
	global_load_lds_dwordx4 v[200:201], off
	s_waitcnt vmcnt(8)
	s_waitcnt lgkmcnt(0)
	s_barrier
	s_setprio 0
	s_waitcnt lgkmcnt(0)
	v_mfma_f32_16x16x32_bf16 v[60:63], v[130:133], v[162:165], 0
	v_mfma_f32_16x16x32_bf16 v[56:59], v[138:141], v[162:165], 0
	v_mfma_f32_16x16x32_bf16 v[44:47], v[130:133], v[170:173], 0
	v_mfma_f32_16x16x32_bf16 v[40:43], v[138:141], v[170:173], 0
	v_mfma_f32_16x16x32_bf16 v[28:31], v[130:133], v[178:181], 0
	v_mfma_f32_16x16x32_bf16 v[24:27], v[138:141], v[178:181], 0
	v_mfma_f32_16x16x32_bf16 v[12:15], v[130:133], v[186:189], 0
	v_mfma_f32_16x16x32_bf16 v[8:11], v[138:141], v[186:189], 0
	v_mfma_f32_16x16x32_bf16 v[60:63], v[134:137], v[166:169], v[60:63]
	v_mfma_f32_16x16x32_bf16 v[56:59], v[142:145], v[166:169], v[56:59]
	v_mfma_f32_16x16x32_bf16 v[44:47], v[134:137], v[174:177], v[44:47]
	v_mfma_f32_16x16x32_bf16 v[40:43], v[142:145], v[174:177], v[40:43]
	v_mfma_f32_16x16x32_bf16 v[28:31], v[134:137], v[182:185], v[28:31]
	v_mfma_f32_16x16x32_bf16 v[24:27], v[142:145], v[182:185], v[24:27]
	v_mfma_f32_16x16x32_bf16 v[12:15], v[134:137], v[190:193], v[12:15]
	v_mfma_f32_16x16x32_bf16 v[8:11], v[142:145], v[190:193], v[8:11]
	s_setprio 0
	s_setprio 0
	v_mfma_f32_16x16x32_bf16 v[52:55], v[146:149], v[162:165], 0
	v_mfma_f32_16x16x32_bf16 v[48:51], v[154:157], v[162:165], 0
	v_mfma_f32_16x16x32_bf16 v[36:39], v[146:149], v[170:173], 0
	v_mfma_f32_16x16x32_bf16 v[32:35], v[154:157], v[170:173], 0
	v_mfma_f32_16x16x32_bf16 v[20:23], v[146:149], v[178:181], 0
	v_mfma_f32_16x16x32_bf16 v[16:19], v[154:157], v[178:181], 0
	v_mfma_f32_16x16x32_bf16 v[4:7], v[146:149], v[186:189], 0
	v_mfma_f32_16x16x32_bf16 v[0:3], v[154:157], v[186:189], 0
	v_mfma_f32_16x16x32_bf16 v[52:55], v[150:153], v[166:169], v[52:55]
	v_mfma_f32_16x16x32_bf16 v[48:51], v[158:161], v[166:169], v[48:51]
	v_mfma_f32_16x16x32_bf16 v[36:39], v[150:153], v[174:177], v[36:39]
	v_mfma_f32_16x16x32_bf16 v[32:35], v[158:161], v[174:177], v[32:35]
	v_mfma_f32_16x16x32_bf16 v[20:23], v[150:153], v[182:185], v[20:23]
	v_mfma_f32_16x16x32_bf16 v[16:19], v[158:161], v[182:185], v[16:19]
	v_mfma_f32_16x16x32_bf16 v[4:7], v[150:153], v[190:193], v[4:7]
	v_mfma_f32_16x16x32_bf16 v[0:3], v[158:161], v[190:193], v[0:3]
	s_setprio 0
	s_barrier
	s_add_i32 s59, 0, 0x18000
	v_add_u32_e32 v84, s59, v237
	v_add_u32_e32 v250, s59, v247
	s_add_i32 s60, 0, 0x1c000
	ds_read_b128 v[130:133], v84
	ds_read_b128 v[134:137], v250
	ds_read_b128 v[138:141], v84 offset:2048
	ds_read_b128 v[142:145], v250 offset:2048
	v_add_u32_e32 v84, s60, v237
	v_add_u32_e32 v251, s60, v247
	ds_read_b128 v[146:149], v84
	ds_read_b128 v[150:153], v251
	ds_read_b128 v[154:157], v84 offset:2048
	ds_read_b128 v[158:161], v251 offset:2048
	s_add_u32 s34, s34, 0x40000
	s_addc_u32 s35, s35, 0
	s_mov_b32 m0, s38
	v_lshl_add_u64 v[84:85], s[34:35], 0, v[210:211]
	ds_read_b128 v[162:165], v241 offset:32768
	ds_read_b128 v[166:169], v246 offset:32768
	ds_read_b128 v[170:173], v241 offset:34816
	ds_read_b128 v[174:177], v246 offset:34816
	ds_read_b128 v[178:181], v241 offset:36864
	ds_read_b128 v[182:185], v246 offset:36864
	ds_read_b128 v[186:189], v241 offset:38912
	ds_read_b128 v[190:193], v246 offset:38912
	global_load_lds_dwordx4 v[84:85], off
	v_lshl_add_u64 v[84:85], s[34:35], 0, v[214:215]
	s_mov_b32 m0, s39
	s_nop 0
	global_load_lds_dwordx4 v[84:85], off
	s_waitcnt vmcnt(8)
	s_waitcnt lgkmcnt(0)
	s_barrier
	s_setprio 0
	s_waitcnt lgkmcnt(0)
	v_mfma_f32_16x16x32_bf16 v[126:129], v[130:133], v[162:165], v[126:129]
	v_mfma_f32_16x16x32_bf16 v[122:125], v[138:141], v[162:165], v[122:125]
	v_mfma_f32_16x16x32_bf16 v[110:113], v[130:133], v[170:173], v[110:113]
	v_mfma_f32_16x16x32_bf16 v[106:109], v[138:141], v[170:173], v[106:109]
	v_mfma_f32_16x16x32_bf16 v[94:97], v[130:133], v[178:181], v[94:97]
	v_mfma_f32_16x16x32_bf16 v[90:93], v[138:141], v[178:181], v[90:93]
	v_mfma_f32_16x16x32_bf16 v[76:79], v[130:133], v[186:189], v[76:79]
	v_mfma_f32_16x16x32_bf16 v[72:75], v[138:141], v[186:189], v[72:75]
	v_mfma_f32_16x16x32_bf16 v[126:129], v[134:137], v[166:169], v[126:129]
	v_mfma_f32_16x16x32_bf16 v[122:125], v[142:145], v[166:169], v[122:125]
	v_mfma_f32_16x16x32_bf16 v[110:113], v[134:137], v[174:177], v[110:113]
	v_mfma_f32_16x16x32_bf16 v[106:109], v[142:145], v[174:177], v[106:109]
	v_mfma_f32_16x16x32_bf16 v[94:97], v[134:137], v[182:185], v[94:97]
	v_mfma_f32_16x16x32_bf16 v[90:93], v[142:145], v[182:185], v[90:93]
	v_mfma_f32_16x16x32_bf16 v[76:79], v[134:137], v[190:193], v[76:79]
	v_mfma_f32_16x16x32_bf16 v[72:75], v[142:145], v[190:193], v[72:75]
	s_setprio 0
	s_setprio 0
	v_mfma_f32_16x16x32_bf16 v[118:121], v[146:149], v[162:165], v[118:121]
	v_mfma_f32_16x16x32_bf16 v[114:117], v[154:157], v[162:165], v[114:117]
	v_mfma_f32_16x16x32_bf16 v[102:105], v[146:149], v[170:173], v[102:105]
	v_mfma_f32_16x16x32_bf16 v[98:101], v[154:157], v[170:173], v[98:101]
	v_mfma_f32_16x16x32_bf16 v[84:87], v[146:149], v[178:181], v[86:89]
	v_mfma_f32_16x16x32_bf16 v[80:83], v[154:157], v[178:181], v[80:83]
	v_mfma_f32_16x16x32_bf16 v[68:71], v[146:149], v[186:189], v[68:71]
	v_mfma_f32_16x16x32_bf16 v[64:67], v[154:157], v[186:189], v[64:67]
	v_mfma_f32_16x16x32_bf16 v[118:121], v[150:153], v[166:169], v[118:121]
	v_mfma_f32_16x16x32_bf16 v[114:117], v[158:161], v[166:169], v[114:117]
	v_mfma_f32_16x16x32_bf16 v[102:105], v[150:153], v[174:177], v[102:105]
	v_mfma_f32_16x16x32_bf16 v[98:101], v[158:161], v[174:177], v[98:101]
	v_mfma_f32_16x16x32_bf16 v[86:89], v[150:153], v[182:185], v[84:87]
	v_mfma_f32_16x16x32_bf16 v[82:85], v[158:161], v[182:185], v[80:83]
	v_mfma_f32_16x16x32_bf16 v[68:71], v[150:153], v[190:193], v[68:71]
	v_mfma_f32_16x16x32_bf16 v[64:67], v[158:161], v[190:193], v[64:67]
	s_setprio 0
	s_barrier
	s_add_i32 s34, s59, s33
	v_lshl_add_u64 v[80:81], v[194:195], 0, s[16:17]
	s_mov_b32 m0, s34
	ds_read_b128 v[162:165], v241 offset:49152
	ds_read_b128 v[166:169], v246 offset:49152
	ds_read_b128 v[170:173], v241 offset:51200
	ds_read_b128 v[174:177], v246 offset:51200
	ds_read_b128 v[178:181], v241 offset:53248
	ds_read_b128 v[182:185], v246 offset:53248
	ds_read_b128 v[186:189], v241 offset:55296
	ds_read_b128 v[190:193], v246 offset:55296
	global_load_lds_dwordx4 v[80:81], off
	s_add_i32 m0, s34, 0x2000
	s_add_u32 s30, s30, 0x40080
	v_lshl_add_u64 v[80:81], v[196:197], 0, s[16:17]
	s_addc_u32 s31, s31, 0
	s_add_i32 s34, s60, s33
	global_load_lds_dwordx4 v[80:81], off
	v_lshl_add_u64 v[80:81], s[30:31], 0, v[212:213]
	s_mov_b32 m0, s34
	s_nop 0
	global_load_lds_dwordx4 v[80:81], off
	v_lshl_add_u64 v[80:81], s[30:31], 0, v[216:217]
	s_add_i32 m0, s34, 0x2000
	s_nop 0
	global_load_lds_dwordx4 v[80:81], off
	v_lshl_add_u64 v[80:81], v[198:199], 0, s[16:17]
	s_mov_b32 m0, s47
	s_nop 0
	global_load_lds_dwordx4 v[80:81], off
	v_lshl_add_u64 v[80:81], v[200:201], 0, s[16:17]
	s_mov_b32 m0, s48
	s_nop 0
	global_load_lds_dwordx4 v[80:81], off
	s_waitcnt vmcnt(8)
	s_waitcnt lgkmcnt(0)
	s_barrier
	s_setprio 0
	s_waitcnt lgkmcnt(0)
	v_mfma_f32_16x16x32_bf16 v[60:63], v[130:133], v[162:165], v[60:63]
	v_mfma_f32_16x16x32_bf16 v[56:59], v[138:141], v[162:165], v[56:59]
	v_mfma_f32_16x16x32_bf16 v[44:47], v[130:133], v[170:173], v[44:47]
	v_mfma_f32_16x16x32_bf16 v[40:43], v[138:141], v[170:173], v[40:43]
	v_mfma_f32_16x16x32_bf16 v[28:31], v[130:133], v[178:181], v[28:31]
	v_mfma_f32_16x16x32_bf16 v[24:27], v[138:141], v[178:181], v[24:27]
	v_mfma_f32_16x16x32_bf16 v[12:15], v[130:133], v[186:189], v[12:15]
	v_mfma_f32_16x16x32_bf16 v[8:11], v[138:141], v[186:189], v[8:11]
	v_mfma_f32_16x16x32_bf16 v[60:63], v[134:137], v[166:169], v[60:63]
	v_mfma_f32_16x16x32_bf16 v[56:59], v[142:145], v[166:169], v[56:59]
	v_mfma_f32_16x16x32_bf16 v[44:47], v[134:137], v[174:177], v[44:47]
	v_mfma_f32_16x16x32_bf16 v[40:43], v[142:145], v[174:177], v[40:43]
	v_mfma_f32_16x16x32_bf16 v[28:31], v[134:137], v[182:185], v[28:31]
	v_mfma_f32_16x16x32_bf16 v[24:27], v[142:145], v[182:185], v[24:27]
	v_mfma_f32_16x16x32_bf16 v[12:15], v[134:137], v[190:193], v[12:15]
	v_mfma_f32_16x16x32_bf16 v[8:11], v[142:145], v[190:193], v[8:11]
	s_setprio 0
	s_setprio 0
	v_mfma_f32_16x16x32_bf16 v[52:55], v[146:149], v[162:165], v[52:55]
	v_mfma_f32_16x16x32_bf16 v[48:51], v[154:157], v[162:165], v[48:51]
	v_mfma_f32_16x16x32_bf16 v[36:39], v[146:149], v[170:173], v[36:39]
	v_mfma_f32_16x16x32_bf16 v[32:35], v[154:157], v[170:173], v[32:35]
	v_mfma_f32_16x16x32_bf16 v[20:23], v[146:149], v[178:181], v[20:23]
	v_mfma_f32_16x16x32_bf16 v[16:19], v[154:157], v[178:181], v[16:19]
	v_mfma_f32_16x16x32_bf16 v[4:7], v[146:149], v[186:189], v[4:7]
	v_mfma_f32_16x16x32_bf16 v[0:3], v[154:157], v[186:189], v[0:3]
	v_mfma_f32_16x16x32_bf16 v[52:55], v[150:153], v[166:169], v[52:55]
	v_mfma_f32_16x16x32_bf16 v[48:51], v[158:161], v[166:169], v[48:51]
	v_mfma_f32_16x16x32_bf16 v[36:39], v[150:153], v[174:177], v[36:39]
	v_mfma_f32_16x16x32_bf16 v[32:35], v[158:161], v[174:177], v[32:35]
	v_mfma_f32_16x16x32_bf16 v[20:23], v[150:153], v[182:185], v[20:23]
	v_mfma_f32_16x16x32_bf16 v[16:19], v[158:161], v[182:185], v[16:19]
	v_mfma_f32_16x16x32_bf16 v[4:7], v[150:153], v[190:193], v[4:7]
	v_mfma_f32_16x16x32_bf16 v[0:3], v[158:161], v[190:193], v[0:3]
	s_setprio 0
	s_barrier
	s_add_i32 s58, s58, 2
	s_add_u32 s28, s28, 0x100
	s_addc_u32 s29, s29, 0
	s_add_u32 s56, s56, 0x100
	s_addc_u32 s57, s57, 0
	s_cmp_gt_u32 s58, 13

.LBB0_1025:
	s_ashr_i32 s23, s22, 31
	s_lshl_b64 s[24:25], s[22:23], 19
	s_add_u32 s24, s90, s24
	s_addc_u32 s25, s91, s25
	s_and_b64 s[26:27], s[6:7], exec
	s_cselect_b32 s23, s25, s35
	s_cselect_b32 s29, s24, s34
	s_ashr_i32 s21, s20, 31
	s_lshl_b64 s[26:27], s[20:21], 19
	s_add_u32 s26, s2, s26
	s_addc_u32 s27, s3, s27
	s_and_b64 s[38:39], s[6:7], exec
	s_cselect_b32 s21, s27, s37
	s_cselect_b32 s55, s26, s36
	s_add_u32 s34, s34, 0x40080
	s_addc_u32 s35, s35, 0
	s_add_u32 s56, s36, 0x100
	s_addc_u32 s57, s37, 0
	s_mov_b32 s58, -2
	s_waitcnt lgkmcnt(0)
	s_waitcnt vmcnt(0)
	v_xor_b32_e32 v246, 64, v189
	v_xor_b32_e32 v247, 64, v185
	v_add_u32_e32 v248, s53, v247
	v_add_u32_e32 v249, s54, v247
	ds_read_b128 v[128:131], v187
	ds_read_b128 v[132:135], v248
	ds_read_b128 v[152:155], v187 offset:2048
	ds_read_b128 v[156:159], v248 offset:2048
	ds_read_b128 v[160:163], v188
	ds_read_b128 v[164:167], v249
	ds_read_b128 v[168:171], v188 offset:2048
	ds_read_b128 v[172:175], v249 offset:2048
	s_add_u32 s36, s34, 0xfffc0080
	s_addc_u32 s37, s35, -1
	s_cmp_eq_u32 s58, 12
	s_cselect_b32 s39, s23, s37
	s_cselect_b32 s38, s29, s36
	s_cselect_b32 s37, s21, s57
	s_cselect_b32 s36, s55, s56
	v_lshl_add_u64 v[216:217], s[34:35], 0, v[144:145]
	s_add_i32 m0, s31, 0xc000
	ds_read_b128 v[176:179], v189
	ds_read_b128 v[180:183], v246
	ds_read_b128 v[192:195], v189 offset:2048
	ds_read_b128 v[196:199], v246 offset:2048
	ds_read_b128 v[200:203], v189 offset:4096
	ds_read_b128 v[204:207], v246 offset:4096
	ds_read_b128 v[208:211], v189 offset:6144
	ds_read_b128 v[212:215], v246 offset:6144
	global_load_lds_dwordx4 v[216:217], off
	v_lshl_add_u64 v[216:217], s[34:35], 0, v[146:147]
	s_add_i32 m0, s31, 0xe000
	s_nop 0
	global_load_lds_dwordx4 v[216:217], off
	s_waitcnt vmcnt(8)
	s_waitcnt lgkmcnt(0)
	s_barrier
	s_setprio 0
	s_waitcnt lgkmcnt(0)
	v_mfma_f32_16x16x32_bf16 v[124:127], v[128:131], v[176:179], 0
	v_mfma_f32_16x16x32_bf16 v[120:123], v[152:155], v[176:179], 0
	v_mfma_f32_16x16x32_bf16 v[108:111], v[128:131], v[192:195], 0
	v_mfma_f32_16x16x32_bf16 v[104:107], v[152:155], v[192:195], 0
	v_mfma_f32_16x16x32_bf16 v[92:95], v[128:131], v[200:203], 0
	v_mfma_f32_16x16x32_bf16 v[88:91], v[152:155], v[200:203], 0
	v_mfma_f32_16x16x32_bf16 v[76:79], v[128:131], v[208:211], 0
	v_mfma_f32_16x16x32_bf16 v[72:75], v[152:155], v[208:211], 0
	v_mfma_f32_16x16x32_bf16 v[124:127], v[132:135], v[180:183], v[124:127]
	v_mfma_f32_16x16x32_bf16 v[120:123], v[156:159], v[180:183], v[120:123]
	v_mfma_f32_16x16x32_bf16 v[108:111], v[132:135], v[196:199], v[108:111]
	v_mfma_f32_16x16x32_bf16 v[104:107], v[156:159], v[196:199], v[104:107]
	v_mfma_f32_16x16x32_bf16 v[92:95], v[132:135], v[204:207], v[92:95]
	v_mfma_f32_16x16x32_bf16 v[88:91], v[156:159], v[204:207], v[88:91]
	v_mfma_f32_16x16x32_bf16 v[76:79], v[132:135], v[212:215], v[76:79]
	v_mfma_f32_16x16x32_bf16 v[72:75], v[156:159], v[212:215], v[72:75]
	s_setprio 0
	s_setprio 0
	v_mfma_f32_16x16x32_bf16 v[116:119], v[160:163], v[176:179], 0
	v_mfma_f32_16x16x32_bf16 v[112:115], v[168:171], v[176:179], 0
	v_mfma_f32_16x16x32_bf16 v[100:103], v[160:163], v[192:195], 0
	v_mfma_f32_16x16x32_bf16 v[96:99], v[168:171], v[192:195], 0
	v_mfma_f32_16x16x32_bf16 v[84:87], v[160:163], v[200:203], 0
	v_mfma_f32_16x16x32_bf16 v[80:83], v[168:171], v[200:203], 0
	v_mfma_f32_16x16x32_bf16 v[68:71], v[160:163], v[208:211], 0
	v_mfma_f32_16x16x32_bf16 v[64:67], v[168:171], v[208:211], 0
	v_mfma_f32_16x16x32_bf16 v[116:119], v[164:167], v[180:183], v[116:119]
	v_mfma_f32_16x16x32_bf16 v[112:115], v[172:175], v[180:183], v[112:115]
	v_mfma_f32_16x16x32_bf16 v[100:103], v[164:167], v[196:199], v[100:103]
	v_mfma_f32_16x16x32_bf16 v[96:99], v[172:175], v[196:199], v[96:99]
	v_mfma_f32_16x16x32_bf16 v[84:87], v[164:167], v[204:207], v[84:87]
	v_mfma_f32_16x16x32_bf16 v[80:83], v[172:175], v[204:207], v[80:83]
	v_mfma_f32_16x16x32_bf16 v[68:71], v[164:167], v[212:215], v[68:71]
	v_mfma_f32_16x16x32_bf16 v[64:67], v[172:175], v[212:215], v[64:67]
	s_setprio 0
	s_barrier
	s_add_i32 s59, s53, s33
	v_lshl_add_u64 v[216:217], s[36:37], 0, v[138:139]
	s_mov_b32 m0, s59
	ds_read_b128 v[176:179], v189 offset:16384
	ds_read_b128 v[180:183], v246 offset:16384
	ds_read_b128 v[192:195], v189 offset:18432
	ds_read_b128 v[196:199], v246 offset:18432
	ds_read_b128 v[200:203], v189 offset:20480
	ds_read_b128 v[204:207], v246 offset:20480
	ds_read_b128 v[208:211], v189 offset:22528
	ds_read_b128 v[212:215], v246 offset:22528
	global_load_lds_dwordx4 v[216:217], off
	s_add_i32 m0, s59, 0x2000
	s_add_u32 s60, s36, 0x40000
	v_lshl_add_u64 v[218:219], s[36:37], 0, v[142:143]
	s_addc_u32 s61, s37, 0
	s_add_i32 s59, s54, s33
	global_load_lds_dwordx4 v[218:219], off
	v_lshl_add_u64 v[220:221], s[60:61], 0, v[138:139]
	s_mov_b32 m0, s59
	v_lshl_add_u64 v[222:223], s[38:39], 0, v[140:141]
	global_load_lds_dwordx4 v[220:221], off
	v_lshl_add_u64 v[220:221], s[60:61], 0, v[142:143]
	s_add_i32 m0, s59, 0x2000
	s_nop 0
	global_load_lds_dwordx4 v[220:221], off
	v_lshl_add_u64 v[220:221], s[38:39], 0, v[136:137]
	s_mov_b32 m0, s31
	s_nop 0
	global_load_lds_dwordx4 v[220:221], off
	s_mov_b32 m0, s40
	s_nop 0
	global_load_lds_dwordx4 v[222:223], off
	s_waitcnt vmcnt(8)
	s_waitcnt lgkmcnt(0)
	s_barrier
	s_setprio 0
	s_waitcnt lgkmcnt(0)
	v_mfma_f32_16x16x32_bf16 v[60:63], v[128:131], v[176:179], 0
	v_mfma_f32_16x16x32_bf16 v[56:59], v[152:155], v[176:179], 0
	v_mfma_f32_16x16x32_bf16 v[44:47], v[128:131], v[192:195], 0
	v_mfma_f32_16x16x32_bf16 v[40:43], v[152:155], v[192:195], 0
	v_mfma_f32_16x16x32_bf16 v[28:31], v[128:131], v[200:203], 0
	v_mfma_f32_16x16x32_bf16 v[24:27], v[152:155], v[200:203], 0
	v_mfma_f32_16x16x32_bf16 v[12:15], v[128:131], v[208:211], 0
	v_mfma_f32_16x16x32_bf16 v[8:11], v[152:155], v[208:211], 0
	v_mfma_f32_16x16x32_bf16 v[60:63], v[132:135], v[180:183], v[60:63]
	v_mfma_f32_16x16x32_bf16 v[56:59], v[156:159], v[180:183], v[56:59]
	v_mfma_f32_16x16x32_bf16 v[44:47], v[132:135], v[196:199], v[44:47]
	v_mfma_f32_16x16x32_bf16 v[40:43], v[156:159], v[196:199], v[40:43]
	v_mfma_f32_16x16x32_bf16 v[28:31], v[132:135], v[204:207], v[28:31]
	v_mfma_f32_16x16x32_bf16 v[24:27], v[156:159], v[204:207], v[24:27]
	v_mfma_f32_16x16x32_bf16 v[12:15], v[132:135], v[212:215], v[12:15]
	v_mfma_f32_16x16x32_bf16 v[8:11], v[156:159], v[212:215], v[8:11]
	s_setprio 0
	s_setprio 0
	v_mfma_f32_16x16x32_bf16 v[52:55], v[160:163], v[176:179], 0
	v_mfma_f32_16x16x32_bf16 v[48:51], v[168:171], v[176:179], 0
	v_mfma_f32_16x16x32_bf16 v[36:39], v[160:163], v[192:195], 0
	v_mfma_f32_16x16x32_bf16 v[32:35], v[168:171], v[192:195], 0
	v_mfma_f32_16x16x32_bf16 v[20:23], v[160:163], v[200:203], 0
	v_mfma_f32_16x16x32_bf16 v[16:19], v[168:171], v[200:203], 0
	v_mfma_f32_16x16x32_bf16 v[4:7], v[160:163], v[208:211], 0
	v_mfma_f32_16x16x32_bf16 v[0:3], v[168:171], v[208:211], 0
	v_mfma_f32_16x16x32_bf16 v[52:55], v[164:167], v[180:183], v[52:55]
	v_mfma_f32_16x16x32_bf16 v[48:51], v[172:175], v[180:183], v[48:51]
	v_mfma_f32_16x16x32_bf16 v[36:39], v[164:167], v[196:199], v[36:39]
	v_mfma_f32_16x16x32_bf16 v[32:35], v[172:175], v[196:199], v[32:35]
	v_mfma_f32_16x16x32_bf16 v[20:23], v[164:167], v[204:207], v[20:23]
	v_mfma_f32_16x16x32_bf16 v[16:19], v[172:175], v[204:207], v[16:19]
	v_mfma_f32_16x16x32_bf16 v[4:7], v[164:167], v[212:215], v[4:7]
	v_mfma_f32_16x16x32_bf16 v[0:3], v[172:175], v[212:215], v[0:3]
	s_setprio 0
	s_barrier
	s_add_i32 s59, 0, 0x18000
	s_add_i32 s60, 0, 0x1c000
	v_add_u32_e32 v156, s59, v185
	v_add_u32_e32 v250, s59, v247
	v_add_u32_e32 v172, s60, v185
	v_add_u32_e32 v251, s60, v247
	ds_read_b128 v[128:131], v156
	ds_read_b128 v[132:135], v250
	ds_read_b128 v[152:155], v156 offset:2048
	ds_read_b128 v[156:159], v250 offset:2048
	ds_read_b128 v[160:163], v172
	ds_read_b128 v[164:167], v251
	ds_read_b128 v[168:171], v172 offset:2048
	ds_read_b128 v[172:175], v251 offset:2048
	s_add_u32 s38, s38, 0x40000
	s_addc_u32 s39, s39, 0
	s_mov_b32 m0, s41
	v_lshl_add_u64 v[224:225], s[38:39], 0, v[136:137]
	ds_read_b128 v[176:179], v189 offset:32768
	ds_read_b128 v[180:183], v246 offset:32768
	ds_read_b128 v[192:195], v189 offset:34816
	ds_read_b128 v[196:199], v246 offset:34816
	ds_read_b128 v[200:203], v189 offset:36864
	ds_read_b128 v[204:207], v246 offset:36864
	ds_read_b128 v[208:211], v189 offset:38912
	ds_read_b128 v[212:215], v246 offset:38912
	global_load_lds_dwordx4 v[224:225], off
	v_lshl_add_u64 v[224:225], s[38:39], 0, v[140:141]
	s_mov_b32 m0, s42
	s_nop 0
	global_load_lds_dwordx4 v[224:225], off
	s_waitcnt vmcnt(8)
	s_waitcnt lgkmcnt(0)
	s_barrier
	s_setprio 0
	s_waitcnt lgkmcnt(0)
	v_mfma_f32_16x16x32_bf16 v[124:127], v[128:131], v[176:179], v[124:127]
	v_mfma_f32_16x16x32_bf16 v[120:123], v[152:155], v[176:179], v[120:123]
	v_mfma_f32_16x16x32_bf16 v[108:111], v[128:131], v[192:195], v[108:111]
	v_mfma_f32_16x16x32_bf16 v[104:107], v[152:155], v[192:195], v[104:107]
	v_mfma_f32_16x16x32_bf16 v[92:95], v[128:131], v[200:203], v[92:95]
	v_mfma_f32_16x16x32_bf16 v[88:91], v[152:155], v[200:203], v[88:91]
	v_mfma_f32_16x16x32_bf16 v[76:79], v[128:131], v[208:211], v[76:79]
	v_mfma_f32_16x16x32_bf16 v[72:75], v[152:155], v[208:211], v[72:75]
	v_mfma_f32_16x16x32_bf16 v[124:127], v[132:135], v[180:183], v[124:127]
	v_mfma_f32_16x16x32_bf16 v[120:123], v[156:159], v[180:183], v[120:123]
	v_mfma_f32_16x16x32_bf16 v[108:111], v[132:135], v[196:199], v[108:111]
	v_mfma_f32_16x16x32_bf16 v[104:107], v[156:159], v[196:199], v[104:107]
	v_mfma_f32_16x16x32_bf16 v[92:95], v[132:135], v[204:207], v[92:95]
	v_mfma_f32_16x16x32_bf16 v[88:91], v[156:159], v[204:207], v[88:91]
	v_mfma_f32_16x16x32_bf16 v[76:79], v[132:135], v[212:215], v[76:79]
	v_mfma_f32_16x16x32_bf16 v[72:75], v[156:159], v[212:215], v[72:75]
	s_setprio 0
	s_setprio 0
	v_mfma_f32_16x16x32_bf16 v[116:119], v[160:163], v[176:179], v[116:119]
	v_mfma_f32_16x16x32_bf16 v[112:115], v[168:171], v[176:179], v[112:115]
	v_mfma_f32_16x16x32_bf16 v[100:103], v[160:163], v[192:195], v[100:103]
	v_mfma_f32_16x16x32_bf16 v[96:99], v[168:171], v[192:195], v[96:99]
	v_mfma_f32_16x16x32_bf16 v[84:87], v[160:163], v[200:203], v[84:87]
	v_mfma_f32_16x16x32_bf16 v[80:83], v[168:171], v[200:203], v[80:83]
	v_mfma_f32_16x16x32_bf16 v[68:71], v[160:163], v[208:211], v[68:71]
	v_mfma_f32_16x16x32_bf16 v[64:67], v[168:171], v[208:211], v[64:67]
	v_mfma_f32_16x16x32_bf16 v[116:119], v[164:167], v[180:183], v[116:119]
	v_mfma_f32_16x16x32_bf16 v[112:115], v[172:175], v[180:183], v[112:115]
	v_mfma_f32_16x16x32_bf16 v[100:103], v[164:167], v[196:199], v[100:103]
	v_mfma_f32_16x16x32_bf16 v[96:99], v[172:175], v[196:199], v[96:99]
	v_mfma_f32_16x16x32_bf16 v[84:87], v[164:167], v[204:207], v[84:87]
	v_mfma_f32_16x16x32_bf16 v[80:83], v[172:175], v[204:207], v[80:83]
	v_mfma_f32_16x16x32_bf16 v[68:71], v[164:167], v[212:215], v[68:71]
	v_mfma_f32_16x16x32_bf16 v[64:67], v[172:175], v[212:215], v[64:67]
	s_setprio 0
	s_barrier
	s_add_i32 s38, s59, s33
	v_lshl_add_u64 v[216:217], v[216:217], 0, s[16:17]
	s_mov_b32 m0, s38
	ds_read_b128 v[176:179], v189 offset:49152
	ds_read_b128 v[180:183], v246 offset:49152
	ds_read_b128 v[192:195], v189 offset:51200
	ds_read_b128 v[196:199], v246 offset:51200
	ds_read_b128 v[200:203], v189 offset:53248
	ds_read_b128 v[204:207], v246 offset:53248
	ds_read_b128 v[208:211], v189 offset:55296
	ds_read_b128 v[212:215], v246 offset:55296
	global_load_lds_dwordx4 v[216:217], off
	s_add_i32 m0, s38, 0x2000
	s_add_u32 s36, s36, 0x40080
	v_lshl_add_u64 v[216:217], v[218:219], 0, s[16:17]
	s_addc_u32 s37, s37, 0
	s_add_i32 s38, s60, s33
	global_load_lds_dwordx4 v[216:217], off
	v_lshl_add_u64 v[216:217], s[36:37], 0, v[138:139]
	s_mov_b32 m0, s38
	s_nop 0
	global_load_lds_dwordx4 v[216:217], off
	v_lshl_add_u64 v[216:217], s[36:37], 0, v[142:143]
	s_add_i32 m0, s38, 0x2000
	s_nop 0
	global_load_lds_dwordx4 v[216:217], off
	v_lshl_add_u64 v[216:217], v[220:221], 0, s[16:17]
	s_mov_b32 m0, s48
	s_nop 0
	global_load_lds_dwordx4 v[216:217], off
	v_lshl_add_u64 v[216:217], v[222:223], 0, s[16:17]
	s_mov_b32 m0, s49
	s_nop 0
	global_load_lds_dwordx4 v[216:217], off
	s_waitcnt vmcnt(8)
	s_waitcnt lgkmcnt(0)
	s_barrier
	s_setprio 0
	s_waitcnt lgkmcnt(0)
	v_mfma_f32_16x16x32_bf16 v[60:63], v[128:131], v[176:179], v[60:63]
	v_mfma_f32_16x16x32_bf16 v[56:59], v[152:155], v[176:179], v[56:59]
	v_mfma_f32_16x16x32_bf16 v[44:47], v[128:131], v[192:195], v[44:47]
	v_mfma_f32_16x16x32_bf16 v[40:43], v[152:155], v[192:195], v[40:43]
	v_mfma_f32_16x16x32_bf16 v[28:31], v[128:131], v[200:203], v[28:31]
	v_mfma_f32_16x16x32_bf16 v[24:27], v[152:155], v[200:203], v[24:27]
	v_mfma_f32_16x16x32_bf16 v[12:15], v[128:131], v[208:211], v[12:15]
	v_mfma_f32_16x16x32_bf16 v[8:11], v[152:155], v[208:211], v[8:11]
	v_mfma_f32_16x16x32_bf16 v[60:63], v[132:135], v[180:183], v[60:63]
	v_mfma_f32_16x16x32_bf16 v[56:59], v[156:159], v[180:183], v[56:59]
	v_mfma_f32_16x16x32_bf16 v[44:47], v[132:135], v[196:199], v[44:47]
	v_mfma_f32_16x16x32_bf16 v[40:43], v[156:159], v[196:199], v[40:43]
	v_mfma_f32_16x16x32_bf16 v[28:31], v[132:135], v[204:207], v[28:31]
	v_mfma_f32_16x16x32_bf16 v[24:27], v[156:159], v[204:207], v[24:27]
	v_mfma_f32_16x16x32_bf16 v[12:15], v[132:135], v[212:215], v[12:15]
	v_mfma_f32_16x16x32_bf16 v[8:11], v[156:159], v[212:215], v[8:11]
	s_setprio 0
	s_setprio 0
	v_mfma_f32_16x16x32_bf16 v[52:55], v[160:163], v[176:179], v[52:55]
	v_mfma_f32_16x16x32_bf16 v[48:51], v[168:171], v[176:179], v[48:51]
	v_mfma_f32_16x16x32_bf16 v[36:39], v[160:163], v[192:195], v[36:39]
	v_mfma_f32_16x16x32_bf16 v[32:35], v[168:171], v[192:195], v[32:35]
	v_mfma_f32_16x16x32_bf16 v[20:23], v[160:163], v[200:203], v[20:23]
	v_mfma_f32_16x16x32_bf16 v[16:19], v[168:171], v[200:203], v[16:19]
	v_mfma_f32_16x16x32_bf16 v[4:7], v[160:163], v[208:211], v[4:7]
	v_mfma_f32_16x16x32_bf16 v[0:3], v[168:171], v[208:211], v[0:3]
	v_mfma_f32_16x16x32_bf16 v[52:55], v[164:167], v[180:183], v[52:55]
	v_mfma_f32_16x16x32_bf16 v[48:51], v[172:175], v[180:183], v[48:51]
	v_mfma_f32_16x16x32_bf16 v[36:39], v[164:167], v[196:199], v[36:39]
	v_mfma_f32_16x16x32_bf16 v[32:35], v[172:175], v[196:199], v[32:35]
	v_mfma_f32_16x16x32_bf16 v[20:23], v[164:167], v[204:207], v[20:23]
	v_mfma_f32_16x16x32_bf16 v[16:19], v[172:175], v[204:207], v[16:19]
	v_mfma_f32_16x16x32_bf16 v[4:7], v[164:167], v[212:215], v[4:7]
	v_mfma_f32_16x16x32_bf16 v[0:3], v[172:175], v[212:215], v[0:3]
	s_setprio 0
	s_barrier
	s_add_i32 s58, s58, 2
	s_add_u32 s34, s34, 0x100
	s_addc_u32 s35, s35, 0
	s_add_u32 s56, s56, 0x100
	s_addc_u32 s57, s57, 0
	s_cmp_gt_u32 s58, 13

.LBB0_1112:
	s_ashr_i32 s17, s16, 31
	s_lshl_b64 s[18:19], s[16:17], 19
	s_add_u32 s18, s2, s18
	s_addc_u32 s19, s3, s19
	s_and_b64 s[20:21], s[0:1], exec
	s_cselect_b32 s17, s19, s25
	s_cselect_b32 s51, s18, s24
	s_ashr_i32 s15, s14, 31
	s_lshl_b64 s[20:21], s[14:15], 19
	s_add_u32 s20, s30, s20
	s_addc_u32 s21, s31, s21
	s_and_b64 s[28:29], s[0:1], exec
	s_cselect_b32 s15, s21, s27
	s_cselect_b32 s52, s20, s26
	s_add_u32 s24, s24, 0x40080
	s_addc_u32 s25, s25, 0
	s_add_u32 s53, s26, 0x100
	s_addc_u32 s54, s27, 0
	s_mov_b32 s55, -2
	s_waitcnt vmcnt(0)
	v_xor_b32_e32 v246, 64, v179
	v_xor_b32_e32 v247, 64, v167
	v_add_u32_e32 v248, s46, v247
	v_add_u32_e32 v249, s47, v247
	ds_read_b128 v[124:127], v171
	ds_read_b128 v[132:135], v248
	ds_read_b128 v[136:139], v171 offset:2048
	ds_read_b128 v[140:143], v248 offset:2048
	ds_read_b128 v[162:165], v175
	ds_read_b128 v[182:185], v249
	ds_read_b128 v[186:189], v175 offset:2048
	ds_read_b128 v[190:193], v249 offset:2048
	s_add_u32 s26, s24, 0xfffc0080
	s_addc_u32 s27, s25, -1
	s_cmp_eq_u32 s55, 12
	s_cselect_b32 s29, s17, s27
	s_cselect_b32 s28, s51, s26
	s_cselect_b32 s27, s15, s54
	s_cselect_b32 s26, s52, s53
	v_lshl_add_u64 v[172:173], s[24:25], 0, v[152:153]
	s_add_i32 m0, s23, 0xc000
	ds_read_b128 v[194:197], v179
	ds_read_b128 v[198:201], v246
	ds_read_b128 v[202:205], v179 offset:2048
	ds_read_b128 v[206:209], v246 offset:2048
	ds_read_b128 v[210:213], v179 offset:4096
	ds_read_b128 v[214:217], v246 offset:4096
	ds_read_b128 v[218:221], v179 offset:6144
	ds_read_b128 v[222:225], v246 offset:6144
	global_load_lds_dwordx4 v[172:173], off
	v_lshl_add_u64 v[172:173], s[24:25], 0, v[154:155]
	s_add_i32 m0, s23, 0xe000
	s_nop 0
	global_load_lds_dwordx4 v[172:173], off
	s_waitcnt vmcnt(8)
	s_waitcnt lgkmcnt(0)
	s_barrier
	s_setprio 0
	s_waitcnt lgkmcnt(0)
	v_mfma_f32_16x16x32_bf16 v[128:131], v[124:127], v[194:197], 0
	v_mfma_f32_16x16x32_bf16 v[120:123], v[136:139], v[194:197], 0
	v_mfma_f32_16x16x32_bf16 v[108:111], v[124:127], v[202:205], 0
	v_mfma_f32_16x16x32_bf16 v[104:107], v[136:139], v[202:205], 0
	v_mfma_f32_16x16x32_bf16 v[92:95], v[124:127], v[210:213], 0
	v_mfma_f32_16x16x32_bf16 v[88:91], v[136:139], v[210:213], 0
	v_mfma_f32_16x16x32_bf16 v[76:79], v[124:127], v[218:221], 0
	v_mfma_f32_16x16x32_bf16 v[72:75], v[136:139], v[218:221], 0
	v_mfma_f32_16x16x32_bf16 v[128:131], v[132:135], v[198:201], v[128:131]
	v_mfma_f32_16x16x32_bf16 v[120:123], v[140:143], v[198:201], v[120:123]
	v_mfma_f32_16x16x32_bf16 v[108:111], v[132:135], v[206:209], v[108:111]
	v_mfma_f32_16x16x32_bf16 v[104:107], v[140:143], v[206:209], v[104:107]
	v_mfma_f32_16x16x32_bf16 v[92:95], v[132:135], v[214:217], v[92:95]
	v_mfma_f32_16x16x32_bf16 v[88:91], v[140:143], v[214:217], v[88:91]
	v_mfma_f32_16x16x32_bf16 v[76:79], v[132:135], v[222:225], v[76:79]
	v_mfma_f32_16x16x32_bf16 v[72:75], v[140:143], v[222:225], v[72:75]
	s_setprio 0
	s_setprio 0
	v_mfma_f32_16x16x32_bf16 v[116:119], v[162:165], v[194:197], 0
	v_mfma_f32_16x16x32_bf16 v[112:115], v[186:189], v[194:197], 0
	v_mfma_f32_16x16x32_bf16 v[100:103], v[162:165], v[202:205], 0
	v_mfma_f32_16x16x32_bf16 v[96:99], v[186:189], v[202:205], 0
	v_mfma_f32_16x16x32_bf16 v[84:87], v[162:165], v[210:213], 0
	v_mfma_f32_16x16x32_bf16 v[80:83], v[186:189], v[210:213], 0
	v_mfma_f32_16x16x32_bf16 v[68:71], v[162:165], v[218:221], 0
	v_mfma_f32_16x16x32_bf16 v[64:67], v[186:189], v[218:221], 0
	v_mfma_f32_16x16x32_bf16 v[116:119], v[182:185], v[198:201], v[116:119]
	v_mfma_f32_16x16x32_bf16 v[112:115], v[190:193], v[198:201], v[112:115]
	v_mfma_f32_16x16x32_bf16 v[100:103], v[182:185], v[206:209], v[100:103]
	v_mfma_f32_16x16x32_bf16 v[96:99], v[190:193], v[206:209], v[96:99]
	v_mfma_f32_16x16x32_bf16 v[84:87], v[182:185], v[214:217], v[84:87]
	v_mfma_f32_16x16x32_bf16 v[80:83], v[190:193], v[214:217], v[80:83]
	v_mfma_f32_16x16x32_bf16 v[68:71], v[182:185], v[222:225], v[68:71]
	v_mfma_f32_16x16x32_bf16 v[64:67], v[190:193], v[222:225], v[64:67]
	s_setprio 0
	s_barrier
	s_add_i32 s56, s46, s33
	v_lshl_add_u64 v[172:173], s[26:27], 0, v[148:149]
	s_mov_b32 m0, s56
	ds_read_b128 v[194:197], v179 offset:16384
	ds_read_b128 v[198:201], v246 offset:16384
	ds_read_b128 v[202:205], v179 offset:18432
	ds_read_b128 v[206:209], v246 offset:18432
	ds_read_b128 v[210:213], v179 offset:20480
	ds_read_b128 v[214:217], v246 offset:20480
	ds_read_b128 v[218:221], v179 offset:22528
	ds_read_b128 v[222:225], v246 offset:22528
	global_load_lds_dwordx4 v[172:173], off
	s_add_i32 m0, s56, 0x2000
	s_add_u32 s56, s26, 0x40000
	v_lshl_add_u64 v[176:177], s[26:27], 0, v[144:145]
	s_addc_u32 s57, s27, 0
	s_add_i32 s58, s47, s33
	global_load_lds_dwordx4 v[176:177], off
	v_lshl_add_u64 v[226:227], s[56:57], 0, v[148:149]
	s_mov_b32 m0, s58
	v_lshl_add_u64 v[228:229], s[28:29], 0, v[146:147]
	global_load_lds_dwordx4 v[226:227], off
	v_lshl_add_u64 v[226:227], s[56:57], 0, v[144:145]
	s_add_i32 m0, s58, 0x2000
	s_nop 0
	global_load_lds_dwordx4 v[226:227], off
	v_lshl_add_u64 v[226:227], s[28:29], 0, v[150:151]
	s_mov_b32 m0, s23
	s_nop 0
	global_load_lds_dwordx4 v[226:227], off
	s_mov_b32 m0, s36
	s_nop 0
	global_load_lds_dwordx4 v[228:229], off
	s_waitcnt vmcnt(8)
	s_waitcnt lgkmcnt(0)
	s_barrier
	s_setprio 0
	s_waitcnt lgkmcnt(0)
	v_mfma_f32_16x16x32_bf16 v[60:63], v[124:127], v[194:197], 0
	v_mfma_f32_16x16x32_bf16 v[56:59], v[136:139], v[194:197], 0
	v_mfma_f32_16x16x32_bf16 v[44:47], v[124:127], v[202:205], 0
	v_mfma_f32_16x16x32_bf16 v[40:43], v[136:139], v[202:205], 0
	v_mfma_f32_16x16x32_bf16 v[28:31], v[124:127], v[210:213], 0
	v_mfma_f32_16x16x32_bf16 v[24:27], v[136:139], v[210:213], 0
	v_mfma_f32_16x16x32_bf16 v[12:15], v[124:127], v[218:221], 0
	v_mfma_f32_16x16x32_bf16 v[8:11], v[136:139], v[218:221], 0
	v_mfma_f32_16x16x32_bf16 v[60:63], v[132:135], v[198:201], v[60:63]
	v_mfma_f32_16x16x32_bf16 v[56:59], v[140:143], v[198:201], v[56:59]
	v_mfma_f32_16x16x32_bf16 v[44:47], v[132:135], v[206:209], v[44:47]
	v_mfma_f32_16x16x32_bf16 v[40:43], v[140:143], v[206:209], v[40:43]
	v_mfma_f32_16x16x32_bf16 v[28:31], v[132:135], v[214:217], v[28:31]
	v_mfma_f32_16x16x32_bf16 v[24:27], v[140:143], v[214:217], v[24:27]
	v_mfma_f32_16x16x32_bf16 v[12:15], v[132:135], v[222:225], v[12:15]
	v_mfma_f32_16x16x32_bf16 v[8:11], v[140:143], v[222:225], v[8:11]
	s_setprio 0
	s_setprio 0
	v_mfma_f32_16x16x32_bf16 v[52:55], v[162:165], v[194:197], 0
	v_mfma_f32_16x16x32_bf16 v[48:51], v[186:189], v[194:197], 0
	v_mfma_f32_16x16x32_bf16 v[36:39], v[162:165], v[202:205], 0
	v_mfma_f32_16x16x32_bf16 v[32:35], v[186:189], v[202:205], 0
	v_mfma_f32_16x16x32_bf16 v[20:23], v[162:165], v[210:213], 0
	v_mfma_f32_16x16x32_bf16 v[16:19], v[186:189], v[210:213], 0
	v_mfma_f32_16x16x32_bf16 v[4:7], v[162:165], v[218:221], 0
	v_mfma_f32_16x16x32_bf16 v[0:3], v[186:189], v[218:221], 0
	v_mfma_f32_16x16x32_bf16 v[52:55], v[182:185], v[198:201], v[52:55]
	v_mfma_f32_16x16x32_bf16 v[48:51], v[190:193], v[198:201], v[48:51]
	v_mfma_f32_16x16x32_bf16 v[36:39], v[182:185], v[206:209], v[36:39]
	v_mfma_f32_16x16x32_bf16 v[32:35], v[190:193], v[206:209], v[32:35]
	v_mfma_f32_16x16x32_bf16 v[20:23], v[182:185], v[214:217], v[20:23]
	v_mfma_f32_16x16x32_bf16 v[16:19], v[190:193], v[214:217], v[16:19]
	v_mfma_f32_16x16x32_bf16 v[4:7], v[182:185], v[222:225], v[4:7]
	v_mfma_f32_16x16x32_bf16 v[0:3], v[190:193], v[222:225], v[0:3]
	s_setprio 0
	s_barrier
	s_add_i32 s56, 0, 0x18000
	s_add_i32 s57, 0, 0x1c000
	v_add_u32_e32 v140, s56, v167
	v_add_u32_e32 v250, s56, v247
	v_add_u32_e32 v160, s57, v167
	v_add_u32_e32 v251, s57, v247
	ds_read_b128 v[124:127], v140
	ds_read_b128 v[132:135], v250
	ds_read_b128 v[136:139], v140 offset:2048
	ds_read_b128 v[140:143], v250 offset:2048
	ds_read_b128 v[162:165], v160
	ds_read_b128 v[182:185], v251
	ds_read_b128 v[186:189], v160 offset:2048
	ds_read_b128 v[190:193], v251 offset:2048
	s_add_u32 s28, s28, 0x40000
	s_addc_u32 s29, s29, 0
	s_mov_b32 m0, s37
	v_lshl_add_u64 v[230:231], s[28:29], 0, v[150:151]
	ds_read_b128 v[194:197], v179 offset:32768
	ds_read_b128 v[198:201], v246 offset:32768
	ds_read_b128 v[202:205], v179 offset:34816
	ds_read_b128 v[206:209], v246 offset:34816
	ds_read_b128 v[210:213], v179 offset:36864
	ds_read_b128 v[214:217], v246 offset:36864
	ds_read_b128 v[218:221], v179 offset:38912
	ds_read_b128 v[222:225], v246 offset:38912
	global_load_lds_dwordx4 v[230:231], off
	v_lshl_add_u64 v[230:231], s[28:29], 0, v[146:147]
	s_mov_b32 m0, s38
	s_nop 0
	global_load_lds_dwordx4 v[230:231], off
	s_waitcnt vmcnt(8)
	s_waitcnt lgkmcnt(0)
	s_barrier
	s_setprio 0
	s_waitcnt lgkmcnt(0)
	v_mfma_f32_16x16x32_bf16 v[128:131], v[124:127], v[194:197], v[128:131]
	v_mfma_f32_16x16x32_bf16 v[120:123], v[136:139], v[194:197], v[120:123]
	v_mfma_f32_16x16x32_bf16 v[108:111], v[124:127], v[202:205], v[108:111]
	v_mfma_f32_16x16x32_bf16 v[104:107], v[136:139], v[202:205], v[104:107]
	v_mfma_f32_16x16x32_bf16 v[92:95], v[124:127], v[210:213], v[92:95]
	v_mfma_f32_16x16x32_bf16 v[88:91], v[136:139], v[210:213], v[88:91]
	v_mfma_f32_16x16x32_bf16 v[76:79], v[124:127], v[218:221], v[76:79]
	v_mfma_f32_16x16x32_bf16 v[72:75], v[136:139], v[218:221], v[72:75]
	v_mfma_f32_16x16x32_bf16 v[128:131], v[132:135], v[198:201], v[128:131]
	v_mfma_f32_16x16x32_bf16 v[120:123], v[140:143], v[198:201], v[120:123]
	v_mfma_f32_16x16x32_bf16 v[108:111], v[132:135], v[206:209], v[108:111]
	v_mfma_f32_16x16x32_bf16 v[104:107], v[140:143], v[206:209], v[104:107]
	v_mfma_f32_16x16x32_bf16 v[92:95], v[132:135], v[214:217], v[92:95]
	v_mfma_f32_16x16x32_bf16 v[88:91], v[140:143], v[214:217], v[88:91]
	v_mfma_f32_16x16x32_bf16 v[76:79], v[132:135], v[222:225], v[76:79]
	v_mfma_f32_16x16x32_bf16 v[72:75], v[140:143], v[222:225], v[72:75]
	s_setprio 0
	s_setprio 0
	v_mfma_f32_16x16x32_bf16 v[116:119], v[162:165], v[194:197], v[116:119]
	v_mfma_f32_16x16x32_bf16 v[112:115], v[186:189], v[194:197], v[112:115]
	v_mfma_f32_16x16x32_bf16 v[100:103], v[162:165], v[202:205], v[100:103]
	v_mfma_f32_16x16x32_bf16 v[96:99], v[186:189], v[202:205], v[96:99]
	v_mfma_f32_16x16x32_bf16 v[84:87], v[162:165], v[210:213], v[84:87]
	v_mfma_f32_16x16x32_bf16 v[80:83], v[186:189], v[210:213], v[80:83]
	v_mfma_f32_16x16x32_bf16 v[68:71], v[162:165], v[218:221], v[68:71]
	v_mfma_f32_16x16x32_bf16 v[64:67], v[186:189], v[218:221], v[64:67]
	v_mfma_f32_16x16x32_bf16 v[116:119], v[182:185], v[198:201], v[116:119]
	v_mfma_f32_16x16x32_bf16 v[112:115], v[190:193], v[198:201], v[112:115]
	v_mfma_f32_16x16x32_bf16 v[100:103], v[182:185], v[206:209], v[100:103]
	v_mfma_f32_16x16x32_bf16 v[96:99], v[190:193], v[206:209], v[96:99]
	v_mfma_f32_16x16x32_bf16 v[84:87], v[182:185], v[214:217], v[84:87]
	v_mfma_f32_16x16x32_bf16 v[80:83], v[190:193], v[214:217], v[80:83]
	v_mfma_f32_16x16x32_bf16 v[68:71], v[182:185], v[222:225], v[68:71]
	v_mfma_f32_16x16x32_bf16 v[64:67], v[190:193], v[222:225], v[64:67]
	s_setprio 0
	s_barrier
	s_add_i32 s28, s56, s33
	v_lshl_add_u64 v[172:173], v[172:173], 0, s[10:11]
	s_mov_b32 m0, s28
	ds_read_b128 v[194:197], v179 offset:49152
	ds_read_b128 v[198:201], v246 offset:49152
	ds_read_b128 v[202:205], v179 offset:51200
	ds_read_b128 v[206:209], v246 offset:51200
	ds_read_b128 v[210:213], v179 offset:53248
	ds_read_b128 v[214:217], v246 offset:53248
	ds_read_b128 v[218:221], v179 offset:55296
	ds_read_b128 v[222:225], v246 offset:55296
	global_load_lds_dwordx4 v[172:173], off
	s_add_i32 m0, s28, 0x2000
	s_add_u32 s26, s26, 0x40080
	v_lshl_add_u64 v[172:173], v[176:177], 0, s[10:11]
	s_addc_u32 s27, s27, 0
	s_add_i32 s28, s57, s33
	global_load_lds_dwordx4 v[172:173], off
	v_lshl_add_u64 v[172:173], s[26:27], 0, v[148:149]
	s_mov_b32 m0, s28
	s_nop 0
	global_load_lds_dwordx4 v[172:173], off
	v_lshl_add_u64 v[172:173], s[26:27], 0, v[144:145]
	s_add_i32 m0, s28, 0x2000
	s_nop 0
	global_load_lds_dwordx4 v[172:173], off
	v_lshl_add_u64 v[172:173], v[226:227], 0, s[10:11]
	s_mov_b32 m0, s43
	s_nop 0
	global_load_lds_dwordx4 v[172:173], off
	v_lshl_add_u64 v[172:173], v[228:229], 0, s[10:11]
	s_mov_b32 m0, s44
	s_nop 0
	global_load_lds_dwordx4 v[172:173], off
	s_waitcnt vmcnt(8)
	s_waitcnt lgkmcnt(0)
	s_barrier
	s_setprio 0
	s_waitcnt lgkmcnt(0)
	v_mfma_f32_16x16x32_bf16 v[60:63], v[124:127], v[194:197], v[60:63]
	v_mfma_f32_16x16x32_bf16 v[56:59], v[136:139], v[194:197], v[56:59]
	v_mfma_f32_16x16x32_bf16 v[44:47], v[124:127], v[202:205], v[44:47]
	v_mfma_f32_16x16x32_bf16 v[40:43], v[136:139], v[202:205], v[40:43]
	v_mfma_f32_16x16x32_bf16 v[28:31], v[124:127], v[210:213], v[28:31]
	v_mfma_f32_16x16x32_bf16 v[24:27], v[136:139], v[210:213], v[24:27]
	v_mfma_f32_16x16x32_bf16 v[12:15], v[124:127], v[218:221], v[12:15]
	v_mfma_f32_16x16x32_bf16 v[8:11], v[136:139], v[218:221], v[8:11]
	v_mfma_f32_16x16x32_bf16 v[60:63], v[132:135], v[198:201], v[60:63]
	v_mfma_f32_16x16x32_bf16 v[56:59], v[140:143], v[198:201], v[56:59]
	v_mfma_f32_16x16x32_bf16 v[44:47], v[132:135], v[206:209], v[44:47]
	v_mfma_f32_16x16x32_bf16 v[40:43], v[140:143], v[206:209], v[40:43]
	v_mfma_f32_16x16x32_bf16 v[28:31], v[132:135], v[214:217], v[28:31]
	v_mfma_f32_16x16x32_bf16 v[24:27], v[140:143], v[214:217], v[24:27]
	v_mfma_f32_16x16x32_bf16 v[12:15], v[132:135], v[222:225], v[12:15]
	v_mfma_f32_16x16x32_bf16 v[8:11], v[140:143], v[222:225], v[8:11]
	s_setprio 0
	s_setprio 0
	v_mfma_f32_16x16x32_bf16 v[52:55], v[162:165], v[194:197], v[52:55]
	v_mfma_f32_16x16x32_bf16 v[48:51], v[186:189], v[194:197], v[48:51]
	v_mfma_f32_16x16x32_bf16 v[36:39], v[162:165], v[202:205], v[36:39]
	v_mfma_f32_16x16x32_bf16 v[32:35], v[186:189], v[202:205], v[32:35]
	v_mfma_f32_16x16x32_bf16 v[20:23], v[162:165], v[210:213], v[20:23]
	v_mfma_f32_16x16x32_bf16 v[16:19], v[186:189], v[210:213], v[16:19]
	v_mfma_f32_16x16x32_bf16 v[4:7], v[162:165], v[218:221], v[4:7]
	v_mfma_f32_16x16x32_bf16 v[0:3], v[186:189], v[218:221], v[0:3]
	v_mfma_f32_16x16x32_bf16 v[52:55], v[182:185], v[198:201], v[52:55]
	v_mfma_f32_16x16x32_bf16 v[48:51], v[190:193], v[198:201], v[48:51]
	v_mfma_f32_16x16x32_bf16 v[36:39], v[182:185], v[206:209], v[36:39]
	v_mfma_f32_16x16x32_bf16 v[32:35], v[190:193], v[206:209], v[32:35]
	v_mfma_f32_16x16x32_bf16 v[20:23], v[182:185], v[214:217], v[20:23]
	v_mfma_f32_16x16x32_bf16 v[16:19], v[190:193], v[214:217], v[16:19]
	v_mfma_f32_16x16x32_bf16 v[4:7], v[182:185], v[222:225], v[4:7]
	v_mfma_f32_16x16x32_bf16 v[0:3], v[190:193], v[222:225], v[0:3]
	s_setprio 0
	s_barrier
	s_add_i32 s55, s55, 2
	s_add_u32 s24, s24, 0x100
	s_addc_u32 s25, s25, 0
	s_add_u32 s53, s53, 0x100
	s_addc_u32 s54, s54, 0
	s_cmp_gt_u32 s55, 13

.LBB0_1195:
	s_add_u32 s41, s16, 0x100
	s_addc_u32 s42, s17, 0
	s_mov_b32 s43, -2
	s_waitcnt vmcnt(0)
	v_xor_b32_e32 v246, 64, v173
	v_xor_b32_e32 v247, 64, v169
	v_add_u32_e32 v248, s35, v247
	v_add_u32_e32 v249, s36, v247
	ds_read_b128 v[144:147], v171
	ds_read_b128 v[148:151], v248
	ds_read_b128 v[152:155], v171 offset:2048
	ds_read_b128 v[156:159], v248 offset:2048
	ds_read_b128 v[160:163], v172
	ds_read_b128 v[164:167], v249
	ds_read_b128 v[174:177], v172 offset:2048
	ds_read_b128 v[178:181], v249 offset:2048
	s_add_u32 s16, s14, 0x100
	s_addc_u32 s17, s15, 0
	s_cmp_eq_u32 s43, 40
	s_cselect_b32 s21, s5, s17
	s_cselect_b32 s20, s4, s16
	s_cselect_b32 s19, s13, s42
	s_cselect_b32 s18, s12, s41
	v_lshl_add_u64 v[214:215], s[14:15], 0, v[136:137]
	s_add_i32 m0, s24, 0xc000
	ds_read_b128 v[182:185], v173
	ds_read_b128 v[186:189], v246
	ds_read_b128 v[190:193], v173 offset:2048
	ds_read_b128 v[194:197], v246 offset:2048
	ds_read_b128 v[198:201], v173 offset:4096
	ds_read_b128 v[202:205], v246 offset:4096
	ds_read_b128 v[206:209], v173 offset:6144
	ds_read_b128 v[210:213], v246 offset:6144
	global_load_lds_dwordx4 v[214:215], off
	v_lshl_add_u64 v[214:215], s[14:15], 0, v[138:139]
	s_add_i32 m0, s24, 0xe000
	s_nop 0
	global_load_lds_dwordx4 v[214:215], off
	s_waitcnt vmcnt(8)
	s_waitcnt lgkmcnt(0)
	s_barrier
	s_setprio 0
	s_waitcnt lgkmcnt(0)
	v_mfma_f32_16x16x32_bf16 v[124:127], v[144:147], v[182:185], 0
	v_mfma_f32_16x16x32_bf16 v[120:123], v[152:155], v[182:185], 0
	v_mfma_f32_16x16x32_bf16 v[112:115], v[144:147], v[190:193], 0
	v_mfma_f32_16x16x32_bf16 v[104:107], v[152:155], v[190:193], 0
	v_mfma_f32_16x16x32_bf16 v[96:99], v[144:147], v[198:201], 0
	v_mfma_f32_16x16x32_bf16 v[88:91], v[152:155], v[198:201], 0
	v_mfma_f32_16x16x32_bf16 v[80:83], v[144:147], v[206:209], 0
	v_mfma_f32_16x16x32_bf16 v[72:75], v[152:155], v[206:209], 0
	v_mfma_f32_16x16x32_bf16 v[124:127], v[148:151], v[186:189], v[124:127]
	v_mfma_f32_16x16x32_bf16 v[120:123], v[156:159], v[186:189], v[120:123]
	v_mfma_f32_16x16x32_bf16 v[112:115], v[148:151], v[194:197], v[112:115]
	v_mfma_f32_16x16x32_bf16 v[104:107], v[156:159], v[194:197], v[104:107]
	v_mfma_f32_16x16x32_bf16 v[96:99], v[148:151], v[202:205], v[96:99]
	v_mfma_f32_16x16x32_bf16 v[88:91], v[156:159], v[202:205], v[88:91]
	v_mfma_f32_16x16x32_bf16 v[80:83], v[148:151], v[210:213], v[80:83]
	v_mfma_f32_16x16x32_bf16 v[72:75], v[156:159], v[210:213], v[72:75]
	s_setprio 0
	s_setprio 0
	v_mfma_f32_16x16x32_bf16 v[116:119], v[160:163], v[182:185], 0
	v_mfma_f32_16x16x32_bf16 v[108:111], v[174:177], v[182:185], 0
	v_mfma_f32_16x16x32_bf16 v[100:103], v[160:163], v[190:193], 0
	v_mfma_f32_16x16x32_bf16 v[92:95], v[174:177], v[190:193], 0
	v_mfma_f32_16x16x32_bf16 v[84:87], v[160:163], v[198:201], 0
	v_mfma_f32_16x16x32_bf16 v[76:79], v[174:177], v[198:201], 0
	v_mfma_f32_16x16x32_bf16 v[68:71], v[160:163], v[206:209], 0
	v_mfma_f32_16x16x32_bf16 v[64:67], v[174:177], v[206:209], 0
	v_mfma_f32_16x16x32_bf16 v[116:119], v[164:167], v[186:189], v[116:119]
	v_mfma_f32_16x16x32_bf16 v[108:111], v[178:181], v[186:189], v[108:111]
	v_mfma_f32_16x16x32_bf16 v[100:103], v[164:167], v[194:197], v[100:103]
	v_mfma_f32_16x16x32_bf16 v[92:95], v[178:181], v[194:197], v[92:95]
	v_mfma_f32_16x16x32_bf16 v[84:87], v[164:167], v[202:205], v[84:87]
	v_mfma_f32_16x16x32_bf16 v[76:79], v[178:181], v[202:205], v[76:79]
	v_mfma_f32_16x16x32_bf16 v[68:71], v[164:167], v[210:213], v[68:71]
	v_mfma_f32_16x16x32_bf16 v[64:67], v[178:181], v[210:213], v[64:67]
	s_setprio 0
	s_barrier
	s_add_i32 s14, s35, s23
	v_lshl_add_u64 v[214:215], s[18:19], 0, v[130:131]
	s_mov_b32 m0, s14
	ds_read_b128 v[182:185], v173 offset:16384
	ds_read_b128 v[186:189], v246 offset:16384
	ds_read_b128 v[190:193], v173 offset:18432
	ds_read_b128 v[194:197], v246 offset:18432
	ds_read_b128 v[198:201], v173 offset:20480
	ds_read_b128 v[202:205], v246 offset:20480
	ds_read_b128 v[206:209], v173 offset:22528
	ds_read_b128 v[210:213], v246 offset:22528
	global_load_lds_dwordx4 v[214:215], off
	s_add_i32 m0, s14, 0x2000
	s_add_u32 s14, s18, 0xb0000
	v_lshl_add_u64 v[216:217], s[18:19], 0, v[134:135]
	s_addc_u32 s15, s19, 0
	s_add_i32 s44, s36, s23
	global_load_lds_dwordx4 v[216:217], off
	v_lshl_add_u64 v[218:219], s[14:15], 0, v[130:131]
	s_mov_b32 m0, s44
	v_lshl_add_u64 v[220:221], s[20:21], 0, v[132:133]
	global_load_lds_dwordx4 v[218:219], off
	v_lshl_add_u64 v[218:219], s[14:15], 0, v[134:135]
	s_add_i32 m0, s44, 0x2000
	s_nop 0
	global_load_lds_dwordx4 v[218:219], off
	v_lshl_add_u64 v[218:219], s[20:21], 0, v[128:129]
	s_mov_b32 m0, s24
	s_nop 0
	global_load_lds_dwordx4 v[218:219], off
	s_mov_b32 m0, s25
	s_nop 0
	global_load_lds_dwordx4 v[220:221], off
	s_waitcnt vmcnt(8)
	s_waitcnt lgkmcnt(0)
	s_barrier
	s_setprio 0
	s_waitcnt lgkmcnt(0)
	v_mfma_f32_16x16x32_bf16 v[60:63], v[144:147], v[182:185], 0
	v_mfma_f32_16x16x32_bf16 v[56:59], v[152:155], v[182:185], 0
	v_mfma_f32_16x16x32_bf16 v[48:51], v[144:147], v[190:193], 0
	v_mfma_f32_16x16x32_bf16 v[40:43], v[152:155], v[190:193], 0
	v_mfma_f32_16x16x32_bf16 v[32:35], v[144:147], v[198:201], 0
	v_mfma_f32_16x16x32_bf16 v[24:27], v[152:155], v[198:201], 0
	v_mfma_f32_16x16x32_bf16 v[16:19], v[144:147], v[206:209], 0
	v_mfma_f32_16x16x32_bf16 v[8:11], v[152:155], v[206:209], 0
	v_mfma_f32_16x16x32_bf16 v[60:63], v[148:151], v[186:189], v[60:63]
	v_mfma_f32_16x16x32_bf16 v[56:59], v[156:159], v[186:189], v[56:59]
	v_mfma_f32_16x16x32_bf16 v[48:51], v[148:151], v[194:197], v[48:51]
	v_mfma_f32_16x16x32_bf16 v[40:43], v[156:159], v[194:197], v[40:43]
	v_mfma_f32_16x16x32_bf16 v[32:35], v[148:151], v[202:205], v[32:35]
	v_mfma_f32_16x16x32_bf16 v[24:27], v[156:159], v[202:205], v[24:27]
	v_mfma_f32_16x16x32_bf16 v[16:19], v[148:151], v[210:213], v[16:19]
	v_mfma_f32_16x16x32_bf16 v[8:11], v[156:159], v[210:213], v[8:11]
	s_setprio 0
	s_setprio 0
	v_mfma_f32_16x16x32_bf16 v[52:55], v[160:163], v[182:185], 0
	v_mfma_f32_16x16x32_bf16 v[44:47], v[174:177], v[182:185], 0
	v_mfma_f32_16x16x32_bf16 v[36:39], v[160:163], v[190:193], 0
	v_mfma_f32_16x16x32_bf16 v[28:31], v[174:177], v[190:193], 0
	v_mfma_f32_16x16x32_bf16 v[20:23], v[160:163], v[198:201], 0
	v_mfma_f32_16x16x32_bf16 v[12:15], v[174:177], v[198:201], 0
	v_mfma_f32_16x16x32_bf16 v[4:7], v[160:163], v[206:209], 0
	v_mfma_f32_16x16x32_bf16 v[0:3], v[174:177], v[206:209], 0
	v_mfma_f32_16x16x32_bf16 v[52:55], v[164:167], v[186:189], v[52:55]
	v_mfma_f32_16x16x32_bf16 v[44:47], v[178:181], v[186:189], v[44:47]
	v_mfma_f32_16x16x32_bf16 v[36:39], v[164:167], v[194:197], v[36:39]
	v_mfma_f32_16x16x32_bf16 v[28:31], v[178:181], v[194:197], v[28:31]
	v_mfma_f32_16x16x32_bf16 v[20:23], v[164:167], v[202:205], v[20:23]
	v_mfma_f32_16x16x32_bf16 v[12:15], v[178:181], v[202:205], v[12:15]
	v_mfma_f32_16x16x32_bf16 v[4:7], v[164:167], v[210:213], v[4:7]
	v_mfma_f32_16x16x32_bf16 v[0:3], v[178:181], v[210:213], v[0:3]
	s_setprio 0
	s_barrier
	s_add_i32 s44, 0, 0x18000
	s_add_i32 s45, 0, 0x1c000
	v_add_u32_e32 v156, s44, v169
	v_add_u32_e32 v250, s44, v247
	v_add_u32_e32 v178, s45, v169
	v_add_u32_e32 v251, s45, v247
	ds_read_b128 v[144:147], v156
	ds_read_b128 v[148:151], v250
	ds_read_b128 v[152:155], v156 offset:2048
	ds_read_b128 v[156:159], v250 offset:2048
	ds_read_b128 v[160:163], v178
	ds_read_b128 v[164:167], v251
	ds_read_b128 v[174:177], v178 offset:2048
	ds_read_b128 v[178:181], v251 offset:2048
	s_add_u32 s14, s20, 0xb0000
	s_addc_u32 s15, s21, 0
	s_mov_b32 m0, s26
	v_lshl_add_u64 v[222:223], s[14:15], 0, v[128:129]
	ds_read_b128 v[182:185], v173 offset:32768
	ds_read_b128 v[186:189], v246 offset:32768
	ds_read_b128 v[190:193], v173 offset:34816
	ds_read_b128 v[194:197], v246 offset:34816
	ds_read_b128 v[198:201], v173 offset:36864
	ds_read_b128 v[202:205], v246 offset:36864
	ds_read_b128 v[206:209], v173 offset:38912
	ds_read_b128 v[210:213], v246 offset:38912
	global_load_lds_dwordx4 v[222:223], off
	v_lshl_add_u64 v[222:223], s[14:15], 0, v[132:133]
	s_mov_b32 m0, s27
	s_nop 0
	global_load_lds_dwordx4 v[222:223], off
	s_waitcnt vmcnt(8)
	s_waitcnt lgkmcnt(0)
	s_barrier
	s_setprio 0
	s_waitcnt lgkmcnt(0)
	v_mfma_f32_16x16x32_bf16 v[124:127], v[144:147], v[182:185], v[124:127]
	v_mfma_f32_16x16x32_bf16 v[120:123], v[152:155], v[182:185], v[120:123]
	v_mfma_f32_16x16x32_bf16 v[112:115], v[144:147], v[190:193], v[112:115]
	v_mfma_f32_16x16x32_bf16 v[104:107], v[152:155], v[190:193], v[104:107]
	v_mfma_f32_16x16x32_bf16 v[96:99], v[144:147], v[198:201], v[96:99]
	v_mfma_f32_16x16x32_bf16 v[88:91], v[152:155], v[198:201], v[88:91]
	v_mfma_f32_16x16x32_bf16 v[80:83], v[144:147], v[206:209], v[80:83]
	v_mfma_f32_16x16x32_bf16 v[72:75], v[152:155], v[206:209], v[72:75]
	v_mfma_f32_16x16x32_bf16 v[124:127], v[148:151], v[186:189], v[124:127]
	v_mfma_f32_16x16x32_bf16 v[120:123], v[156:159], v[186:189], v[120:123]
	v_mfma_f32_16x16x32_bf16 v[112:115], v[148:151], v[194:197], v[112:115]
	v_mfma_f32_16x16x32_bf16 v[104:107], v[156:159], v[194:197], v[104:107]
	v_mfma_f32_16x16x32_bf16 v[96:99], v[148:151], v[202:205], v[96:99]
	v_mfma_f32_16x16x32_bf16 v[88:91], v[156:159], v[202:205], v[88:91]
	v_mfma_f32_16x16x32_bf16 v[80:83], v[148:151], v[210:213], v[80:83]
	v_mfma_f32_16x16x32_bf16 v[72:75], v[156:159], v[210:213], v[72:75]
	s_setprio 0
	s_setprio 0
	v_mfma_f32_16x16x32_bf16 v[116:119], v[160:163], v[182:185], v[116:119]
	v_mfma_f32_16x16x32_bf16 v[108:111], v[174:177], v[182:185], v[108:111]
	v_mfma_f32_16x16x32_bf16 v[100:103], v[160:163], v[190:193], v[100:103]
	v_mfma_f32_16x16x32_bf16 v[92:95], v[174:177], v[190:193], v[92:95]
	v_mfma_f32_16x16x32_bf16 v[84:87], v[160:163], v[198:201], v[84:87]
	v_mfma_f32_16x16x32_bf16 v[76:79], v[174:177], v[198:201], v[76:79]
	v_mfma_f32_16x16x32_bf16 v[68:71], v[160:163], v[206:209], v[68:71]
	v_mfma_f32_16x16x32_bf16 v[64:67], v[174:177], v[206:209], v[64:67]
	v_mfma_f32_16x16x32_bf16 v[116:119], v[164:167], v[186:189], v[116:119]
	v_mfma_f32_16x16x32_bf16 v[108:111], v[178:181], v[186:189], v[108:111]
	v_mfma_f32_16x16x32_bf16 v[100:103], v[164:167], v[194:197], v[100:103]
	v_mfma_f32_16x16x32_bf16 v[92:95], v[178:181], v[194:197], v[92:95]
	v_mfma_f32_16x16x32_bf16 v[84:87], v[164:167], v[202:205], v[84:87]
	v_mfma_f32_16x16x32_bf16 v[76:79], v[178:181], v[202:205], v[76:79]
	v_mfma_f32_16x16x32_bf16 v[68:71], v[164:167], v[210:213], v[68:71]
	v_mfma_f32_16x16x32_bf16 v[64:67], v[178:181], v[210:213], v[64:67]
	s_setprio 0
	s_barrier
	s_add_i32 s14, s44, s23
	v_lshl_add_u64 v[214:215], v[214:215], 0, s[8:9]
	s_mov_b32 m0, s14
	ds_read_b128 v[182:185], v173 offset:49152
	ds_read_b128 v[186:189], v246 offset:49152
	ds_read_b128 v[190:193], v173 offset:51200
	ds_read_b128 v[194:197], v246 offset:51200
	ds_read_b128 v[198:201], v173 offset:53248
	ds_read_b128 v[202:205], v246 offset:53248
	ds_read_b128 v[206:209], v173 offset:55296
	ds_read_b128 v[210:213], v246 offset:55296
	global_load_lds_dwordx4 v[214:215], off
	s_add_i32 m0, s14, 0x2000
	s_add_u32 s14, s18, 0xb0080
	v_lshl_add_u64 v[214:215], v[216:217], 0, s[8:9]
	s_addc_u32 s15, s19, 0
	s_add_i32 s18, s45, s23
	global_load_lds_dwordx4 v[214:215], off
	v_lshl_add_u64 v[214:215], s[14:15], 0, v[130:131]
	s_mov_b32 m0, s18
	s_nop 0
	global_load_lds_dwordx4 v[214:215], off
	v_lshl_add_u64 v[214:215], s[14:15], 0, v[134:135]
	s_add_i32 m0, s18, 0x2000
	s_nop 0
	global_load_lds_dwordx4 v[214:215], off
	v_lshl_add_u64 v[214:215], v[218:219], 0, s[8:9]
	s_mov_b32 m0, s31
	s_nop 0
	global_load_lds_dwordx4 v[214:215], off
	v_lshl_add_u64 v[214:215], v[220:221], 0, s[8:9]
	s_mov_b32 m0, s33
	s_nop 0
	global_load_lds_dwordx4 v[214:215], off
	s_waitcnt vmcnt(8)
	s_waitcnt lgkmcnt(0)
	s_barrier
	s_setprio 0
	s_waitcnt lgkmcnt(0)
	v_mfma_f32_16x16x32_bf16 v[60:63], v[144:147], v[182:185], v[60:63]
	v_mfma_f32_16x16x32_bf16 v[56:59], v[152:155], v[182:185], v[56:59]
	v_mfma_f32_16x16x32_bf16 v[48:51], v[144:147], v[190:193], v[48:51]
	v_mfma_f32_16x16x32_bf16 v[40:43], v[152:155], v[190:193], v[40:43]
	v_mfma_f32_16x16x32_bf16 v[32:35], v[144:147], v[198:201], v[32:35]
	v_mfma_f32_16x16x32_bf16 v[24:27], v[152:155], v[198:201], v[24:27]
	v_mfma_f32_16x16x32_bf16 v[16:19], v[144:147], v[206:209], v[16:19]
	v_mfma_f32_16x16x32_bf16 v[8:11], v[152:155], v[206:209], v[8:11]
	v_mfma_f32_16x16x32_bf16 v[60:63], v[148:151], v[186:189], v[60:63]
	v_mfma_f32_16x16x32_bf16 v[56:59], v[156:159], v[186:189], v[56:59]
	v_mfma_f32_16x16x32_bf16 v[48:51], v[148:151], v[194:197], v[48:51]
	v_mfma_f32_16x16x32_bf16 v[40:43], v[156:159], v[194:197], v[40:43]
	v_mfma_f32_16x16x32_bf16 v[32:35], v[148:151], v[202:205], v[32:35]
	v_mfma_f32_16x16x32_bf16 v[24:27], v[156:159], v[202:205], v[24:27]
	v_mfma_f32_16x16x32_bf16 v[16:19], v[148:151], v[210:213], v[16:19]
	v_mfma_f32_16x16x32_bf16 v[8:11], v[156:159], v[210:213], v[8:11]
	s_setprio 0
	s_setprio 0
	v_mfma_f32_16x16x32_bf16 v[52:55], v[160:163], v[182:185], v[52:55]
	v_mfma_f32_16x16x32_bf16 v[44:47], v[174:177], v[182:185], v[44:47]
	v_mfma_f32_16x16x32_bf16 v[36:39], v[160:163], v[190:193], v[36:39]
	v_mfma_f32_16x16x32_bf16 v[28:31], v[174:177], v[190:193], v[28:31]
	v_mfma_f32_16x16x32_bf16 v[20:23], v[160:163], v[198:201], v[20:23]
	v_mfma_f32_16x16x32_bf16 v[12:15], v[174:177], v[198:201], v[12:15]
	v_mfma_f32_16x16x32_bf16 v[4:7], v[160:163], v[206:209], v[4:7]
	v_mfma_f32_16x16x32_bf16 v[0:3], v[174:177], v[206:209], v[0:3]
	v_mfma_f32_16x16x32_bf16 v[52:55], v[164:167], v[186:189], v[52:55]
	v_mfma_f32_16x16x32_bf16 v[44:47], v[178:181], v[186:189], v[44:47]
	v_mfma_f32_16x16x32_bf16 v[36:39], v[164:167], v[194:197], v[36:39]
	v_mfma_f32_16x16x32_bf16 v[28:31], v[178:181], v[194:197], v[28:31]
	v_mfma_f32_16x16x32_bf16 v[20:23], v[164:167], v[202:205], v[20:23]
	v_mfma_f32_16x16x32_bf16 v[12:15], v[178:181], v[202:205], v[12:15]
	v_mfma_f32_16x16x32_bf16 v[4:7], v[164:167], v[210:213], v[4:7]
	v_mfma_f32_16x16x32_bf16 v[0:3], v[178:181], v[210:213], v[0:3]
	s_setprio 0
	s_barrier
	s_add_i32 s43, s43, 2
	s_add_u32 s41, s41, 0x100
	s_addc_u32 s42, s42, 0
	s_cmp_gt_u32 s43, 41
	s_mov_b64 s[14:15], s[16:17]
